# cross-attention output stores: half-sector dwordx4 (32 rows x 32 B) -> full-sector dwordx4 (16 rows x 64 B) with an extra v_permlane16_swap stage on the packed dwords
# speedup vs baseline: 1.0053x; 1.0053x over previous
; DI int tidx() { int t = threadIdx.x; asm volatile("" : "+v"(t)); return t; }
; DI void xattn_unit(const bf16_t* __restrict__ Qg, const bf16_t* __restrict__ Kg, const bf16_t* __restrict__ Vg, bf16_t* __restrict__ Og, lds_t* shm) {
;   constexpr int LDQ = DM, LDKV = 2048, NC = 8;
;   const int tid = tidx(), lane = tid & 63, h = lane >> 5, l31 = lane & 31, wid = __builtin_amdgcn_readfirstlane(tid >> 6);
;   unsigned soff[2];
; #pragma unroll
;   for (int i = 0; i < 2; ++i) { unsigned r, c; inv_off_a(tid + 512 * i, r, c); soff[i] = (r * (unsigned)LDKV + c * 8u) * 2u; }
;   constexpr unsigned tstep = 64u * LDKV * 2u;
;   auto issue_tile = [&](const bf16_t* src, int t, unsigned lds_base) __attribute__((always_inline)) {
;     const char* sb = (const char*)src + (size_t)t * tstep; lds_t* base = shm + lds_base + wid * 1024;
; #pragma unroll
;     for (int im = 0; im < 2; ++im) { glds16(sb + im * 256, soff[0], base + im * 16384); glds16(sb + im * 256, soff[1], base + im * 16384 + 8192); }
;   };
;   __syncthreads();
; #pragma unroll
;   for (int t = 0; t < 4; ++t) issue_tile(Kg, t, t * 32768);
;   issue_tile(Vg, 0, 131072);
;   const unsigned q4 = (lane & 15) >> 2, pp = lane & 3, blk = (lane >> 4) & 1;
;   const unsigned xk = (l31 >> 2) & 3, kbase = 2048u * (l31 >> 3) + 64u * (l31 & 7);
;   const unsigned ka0 = kbase + 16u * ((unsigned)h ^ xk), ka2 = kbase + 16u * ((2u + h) ^ xk);
;   const unsigned vrow = 64u * (4u * h + q4), cl = 2u * blk + (pp >> 1);
;   const unsigned va0 = vrow + 16u * (cl ^ (unsigned)h) + 8u * (pp & 1), va1 = vrow + 16u * (cl ^ ((unsigned)h ^ 2u)) + 8u * (pp & 1);
;   const unsigned qoff = ((unsigned)l31 * (unsigned)LDQ + 8u * h) * 2u;
;   f32x16 S[4][2];
; #pragma unroll
;   for (int t = 0; t < 4; ++t)
; #pragma unroll
;     for (int kb = 0; kb < 2; ++kb)
; #pragma unroll
;       for (int i = 0; i < 16; ++i) S[t][kb][i] = 0.f;
;   asm volatile("s_waitcnt vmcnt(0)" ::: "memory");
;   __syncthreads();
; DI void cross_attn_own_tiles(const Params& p, lds_t* shm) {
;     ...
;   for (int i = 0;; ++i) {
;     int pm, pn; if (!g8::tile_coords(i * (int)gridDim.x + (int)blockIdx.x, T_TOK / 256, 4, pm, pn)) break;
;     const int b = pm >> 5, hd = pn; const size_t r0 = (size_t)pm * 256 + wid * 32;
;     xattn_unit(Q + r0 * DM + hd * 256, KV + (size_t)b * 256 * 2048 + hd * 256, KV + (size_t)b * 256 * 2048 + 1024 + hd * 256, O + r0 * DM + hd * 256, shm);
.LBB0_629:
	s_add_i32 s0, s29, s0
	s_ashr_i32 s1, s0, 31
	s_lshr_b32 s1, s1, 27
	s_add_i32 s1, s0, s1
	s_ashr_i32 s28, s1, 5
	s_and_b32 s1, s1, 0xffe0
	s_sub_i32 s0, s0, s1
	s_bfe_i32 s1, s0, 0x80000
	s_bfe_u32 s1, s1, 0x3000c
	s_add_i32 s1, s0, s1
	s_bfe_i32 s29, s1, 0x80000
	s_and_b32 s1, s1, 0xf8
	s_sub_i32 s0, s0, s1
	s_lshl_b32 s28, s28, 3
	s_sext_i32_i8 s0, s0
	s_add_i32 s0, s28, s0
	s_ashr_i32 s1, s0, 31
	s_ashr_i32 s28, s0, 5
	s_lshl_b64 s[0:1], s[0:1], 18
	s_add_u32 s0, s0, s4
	s_addc_u32 s1, s1, s5
	s_lshl_b64 s[0:1], s[0:1], 1
	s_sext_i32_i16 s29, s29
	s_add_u32 s36, s26, s0
	s_addc_u32 s37, s27, s1
	s_lshl_b32 s29, s29, 5
	s_and_b32 s30, s29, 0xffffff00
	s_ashr_i32 s31, s30, 31
	s_lshl_b64 s[30:31], s[30:31], 1
	s_add_u32 s38, s36, s30
	s_addc_u32 s39, s37, s31
	s_ashr_i32 s29, s28, 31
	s_lshl_b64 s[28:29], s[28:29], 20
	s_add_u32 s28, s50, s28
	s_addc_u32 s29, s51, s29
	s_add_u32 s36, s28, s30
	s_addc_u32 s37, s29, s31
	s_add_u32 s0, s44, s0
	s_addc_u32 s1, s45, s1
	s_add_u32 s30, s0, s30
	v_mov_b32_e32 v6, v212
	s_addc_u32 s31, s1, s31
	s_mov_b32 s1, 0xfffff8
	v_bfe_u32 v1, v6, 2, 3
	v_lshrrev_b32_e32 v2, 4, v6
	v_and_or_b32 v2, v2, s1, v1
	v_lshrrev_b32_e32 v8, 3, v6
	v_lshrrev_b32_e32 v3, 2, v2
	v_and_b32_e32 v0, 12, v8
	v_xor_b32_e32 v3, v3, v6
	v_lshlrev_b32_e32 v7, 4, v6
	v_and_or_b32 v3, v3, 3, v0
	v_lshlrev_b32_e32 v2, 12, v2
	v_lshl_or_b32 v160, v3, 4, v2
	v_add_u32_e32 v2, 0x2000, v7
	v_readfirstlane_b32 s0, v6
	v_lshrrev_b32_e32 v2, 8, v2
	v_and_or_b32 v1, v2, s1, v1
	s_lshl_b32 s0, s0, 4
	v_lshrrev_b32_e32 v2, 2, v1
	s_and_b32 s82, s0, 0xfffffc00
	v_xor_b32_e32 v2, v2, v6
	s_add_i32 s78, s82, 0
	v_and_or_b32 v0, v2, 3, v0
	v_lshlrev_b32_e32 v1, 12, v1
	s_mov_b32 m0, s78
	v_lshl_or_b32 v162, v0, 4, v1
	s_barrier
	v_lshl_add_u64 v[0:1], s[36:37], 0, v[160:161]
	global_load_lds_dwordx4 v160, s[36:37]
	s_add_i32 m0, s78, 0x2000
	s_mov_b64 s[0:1], 0x100
	global_load_lds_dwordx4 v162, s[36:37]
	s_add_i32 m0, s78, 0x4000
	v_lshl_add_u64 v[4:5], v[0:1], 0, s[0:1]
	v_mov_b32_e32 v163, v161
	global_load_lds_dwordx4 v[4:5], off
	s_add_i32 m0, s78, 0x6000
	v_lshl_add_u64 v[2:3], s[36:37], 0, v[162:163]
	s_add_u32 s28, s36, 0x40000
	v_lshl_add_u64 v[4:5], v[2:3], 0, s[0:1]
	s_addc_u32 s29, s37, 0
	s_add_i32 s67, s78, 0x8000
	global_load_lds_dwordx4 v[4:5], off
	s_mov_b32 m0, s67
	s_add_i32 s0, s78, 0xa000
	global_load_lds_dwordx4 v160, s[28:29]
	s_mov_b32 m0, s0
	v_bfe_u32 v163, v6, 5, 1
	global_load_lds_dwordx4 v162, s[28:29]
	s_add_u32 s28, s36, 0x40100
	s_addc_u32 s29, s37, 0
	s_add_i32 s1, s78, 0xc000
	s_add_i32 vcc_lo, s78, 0xe000
	s_mov_b32 m0, s1
	s_add_u32 s68, s36, 0x80000
	global_load_lds_dwordx4 v160, s[28:29]
	s_mov_b32 m0, vcc_lo
	s_addc_u32 s69, s37, 0
	s_add_i32 vcc_hi, s78, 0x10000
	global_load_lds_dwordx4 v162, s[28:29]
	s_mov_b32 m0, vcc_hi
	s_add_i32 s28, s78, 0x12000
	global_load_lds_dwordx4 v160, s[68:69]
	s_mov_b32 m0, s28
	s_add_u32 s76, s36, 0x80100
	global_load_lds_dwordx4 v162, s[68:69]
	s_addc_u32 s77, s37, 0
	s_add_i32 s29, s78, 0x14000
	s_add_i32 s68, s78, 0x16000
	s_mov_b32 m0, s29
	s_add_u32 s80, s36, 0xc0000
	global_load_lds_dwordx4 v160, s[76:77]
	s_mov_b32 m0, s68
	s_addc_u32 s81, s37, 0
	s_add_i32 s69, s78, 0x18000
	global_load_lds_dwordx4 v162, s[76:77]
	s_mov_b32 m0, s69
	s_add_i32 s76, s78, 0x1a000
	global_load_lds_dwordx4 v160, s[80:81]
	s_mov_b32 m0, s76
	v_and_b32_e32 v132, 0xc0, v7
	global_load_lds_dwordx4 v162, s[80:81]
	s_add_u32 s80, s36, 0xc0100
	s_addc_u32 s81, s37, 0
	s_add_i32 s77, s78, 0x1c000
	s_mov_b32 m0, s77
	s_add_i32 s78, s78, 0x1e000
	global_load_lds_dwordx4 v160, s[80:81]
	s_mov_b32 m0, s78
	s_add_i32 s79, s14, s82
	global_load_lds_dwordx4 v162, s[80:81]
	s_mov_b64 s[80:81], 0x800
	v_lshl_add_u64 v[4:5], v[0:1], 0, s[80:81]
	s_mov_b32 m0, s79
	v_or_b32_e32 v7, 2, v163
	global_load_lds_dwordx4 v[4:5], off
	s_add_i32 m0, s79, 0x2000
	v_lshl_add_u64 v[4:5], v[2:3], 0, s[80:81]
	s_mov_b64 s[80:81], 0x900
	global_load_lds_dwordx4 v[4:5], off
	s_add_i32 m0, s79, 0x4000
	v_lshl_add_u64 v[0:1], v[0:1], 0, s[80:81]
	global_load_lds_dwordx4 v[0:1], off
	s_add_i32 m0, s79, 0x6000
	v_lshl_add_u64 v[0:1], v[2:3], 0, s[80:81]
	global_load_lds_dwordx4 v[0:1], off
	v_lshlrev_b32_e32 v1, 6, v6
	v_and_b32_e32 v5, 0x1c0, v1
	v_and_b32_e32 v1, 2, v8
	v_bfe_u32 v2, v6, 1, 1
	v_bitop3_b32 v3, v1, v163, v2 bitop3:0x36
	v_bitop3_b32 v1, v1, v7, v2 bitop3:0x36
	s_waitcnt vmcnt(0)
	v_lshlrev_b32_e32 v165, 4, v1
	v_lshlrev_b32_e32 v1, 11, v6
	v_lshlrev_b32_e32 v0, 8, v6
	v_and_b32_e32 v164, 0xf800, v1
	v_lshrrev_b32_e32 v4, 5, v6
	v_lshlrev_b32_e32 v169, 3, v6
	v_bfe_u32 v130, v6, 2, 2
	v_and_b32_e32 v6, 0x1800, v0
	v_lshlrev_b32_e32 v166, 4, v3
	v_lshl_or_b32 v128, v163, 4, v164
	s_waitcnt vmcnt(0) lgkmcnt(0)
	s_barrier
; #define LDSP(T, p) ((__attribute__((address_space(3))) T*)(p))
; #define MFMA32(a, b, c) __builtin_amdgcn_mfma_f32_32x32x16_bf16((a), (b), (c), 0, 0, 0)
; DI void xattn_unit(const bf16_t* __restrict__ Qg, const bf16_t* __restrict__ Kg, const bf16_t* __restrict__ Vg, bf16_t* __restrict__ Og, lds_t* shm) {
;     ...
; #pragma unroll
;   for (int ss = 0; ss < 16; ++ss) {
;     const int cgl = 2 * ss, img = cgl >> 4;
;     const bf16x8 qv = gld<bf16x8>(Qg + 16 * ss, qoff);
; #pragma unroll
;     for (int t = 0; t < 4; ++t)
; #pragma unroll
;       for (int kb = 0; kb < 2; ++kb) {
;         const bf16x8 kf = *LDSP(const bf16x8, shm + t * 32768 + img * 16384 + kb * 8192 + 512 * ((cgl & 15) >> 2) + ((cgl & 2) ? ka2 : ka0));
;         S[t][kb] = MFMA32(kf, qv, S[t][kb]);
;       }
;   }
	global_load_dwordx4 v[172:175], v128, s[38:39]
	global_load_dwordx4 v[176:179], v128, s[38:39] offset:32
	global_load_dwordx4 v[180:183], v128, s[38:39] offset:64
	global_load_dwordx4 v[184:187], v128, s[38:39] offset:96
	global_load_dwordx4 v[188:191], v128, s[38:39] offset:128
	global_load_dwordx4 v[192:195], v128, s[38:39] offset:160
	global_load_dwordx4 v[196:199], v128, s[38:39] offset:192
	global_load_dwordx4 v[200:203], v128, s[38:39] offset:224
	global_load_dwordx4 v[204:207], v128, s[38:39] offset:256
	global_load_dwordx4 v[208:211], v128, s[38:39] offset:288
	global_load_dwordx4 v[216:219], v128, s[38:39] offset:320
	global_load_dwordx4 v[220:223], v128, s[38:39] offset:352
	global_load_dwordx4 v[224:227], v128, s[38:39] offset:384
	global_load_dwordx4 v[228:231], v128, s[38:39] offset:416
	global_load_dwordx4 v[232:235], v128, s[38:39] offset:448
	global_load_dwordx4 v[236:239], v128, s[38:39] offset:480
	v_bitop3_b32 v4, v4, v130, 1 bitop3:0x6c
	v_add3_u32 v131, 0, v6, v5
	v_lshl_add_u32 v129, v4, 4, v131
	v_bitop3_b32 v130, v163, v130, 2 bitop3:0x36
	v_lshl_add_u32 v133, v130, 4, v131
	v_lshl_or_b32 v170, v163, 8, v132
	v_add_u32_e32 v248, 0x10000, v129
	v_add_u32_e32 v249, 0x10000, v133
	ds_read_b128 v[144:147], v129
	ds_read_b128 v[148:151], v129 offset:8192
	ds_read_b128 v[152:155], v129 offset:32768
	ds_read_b128 v[156:159], v129 offset:40960
	s_waitcnt vmcnt(15) lgkmcnt(3)
	v_mfma_f32_32x32x16_bf16 v[112:127], v[144:147], v[172:175], 0
	ds_read_b128 v[144:147], v248
	s_waitcnt lgkmcnt(3)
	v_mfma_f32_32x32x16_bf16 v[96:111], v[148:151], v[172:175], 0
	ds_read_b128 v[148:151], v248 offset:8192
	s_waitcnt lgkmcnt(3)
	v_mfma_f32_32x32x16_bf16 v[80:95], v[152:155], v[172:175], 0
	ds_read_b128 v[152:155], v248 offset:32768
	s_waitcnt lgkmcnt(3)
	v_mfma_f32_32x32x16_bf16 v[64:79], v[156:159], v[172:175], 0
	ds_read_b128 v[156:159], v248 offset:40960
	s_waitcnt lgkmcnt(3)
	v_mfma_f32_32x32x16_bf16 v[48:63], v[144:147], v[172:175], 0
	ds_read_b128 v[144:147], v133
	s_waitcnt lgkmcnt(3)
	v_mfma_f32_32x32x16_bf16 v[32:47], v[148:151], v[172:175], 0
	ds_read_b128 v[148:151], v133 offset:8192
	s_waitcnt lgkmcnt(3)
	v_mfma_f32_32x32x16_bf16 v[16:31], v[152:155], v[172:175], 0
	ds_read_b128 v[152:155], v133 offset:32768
	s_waitcnt lgkmcnt(3)
	v_mfma_f32_32x32x16_bf16 v[0:15], v[156:159], v[172:175], 0
	ds_read_b128 v[156:159], v133 offset:40960
	s_waitcnt vmcnt(14) lgkmcnt(3)
	v_mfma_f32_32x32x16_bf16 v[112:127], v[144:147], v[176:179], v[112:127]
	ds_read_b128 v[144:147], v249
	s_waitcnt lgkmcnt(3)
	v_mfma_f32_32x32x16_bf16 v[96:111], v[148:151], v[176:179], v[96:111]
	ds_read_b128 v[148:151], v249 offset:8192
	s_waitcnt lgkmcnt(3)
	v_mfma_f32_32x32x16_bf16 v[80:95], v[152:155], v[176:179], v[80:95]
	ds_read_b128 v[152:155], v249 offset:32768
	s_waitcnt lgkmcnt(3)
	v_mfma_f32_32x32x16_bf16 v[64:79], v[156:159], v[176:179], v[64:79]
	ds_read_b128 v[156:159], v249 offset:40960
	s_waitcnt lgkmcnt(3)
	v_mfma_f32_32x32x16_bf16 v[48:63], v[144:147], v[176:179], v[48:63]
	ds_read_b128 v[144:147], v129 offset:512
	s_waitcnt lgkmcnt(3)
	v_mfma_f32_32x32x16_bf16 v[32:47], v[148:151], v[176:179], v[32:47]
	ds_read_b128 v[148:151], v129 offset:8704
	s_waitcnt lgkmcnt(3)
	v_mfma_f32_32x32x16_bf16 v[16:31], v[152:155], v[176:179], v[16:31]
	ds_read_b128 v[152:155], v129 offset:33280
	s_waitcnt lgkmcnt(3)
	v_mfma_f32_32x32x16_bf16 v[0:15], v[156:159], v[176:179], v[0:15]
	ds_read_b128 v[156:159], v129 offset:41472
	s_waitcnt vmcnt(13) lgkmcnt(3)
	v_mfma_f32_32x32x16_bf16 v[112:127], v[144:147], v[180:183], v[112:127]
	ds_read_b128 v[144:147], v248 offset:512
	s_waitcnt lgkmcnt(3)
	v_mfma_f32_32x32x16_bf16 v[96:111], v[148:151], v[180:183], v[96:111]
	ds_read_b128 v[148:151], v248 offset:8704
	s_waitcnt lgkmcnt(3)
	v_mfma_f32_32x32x16_bf16 v[80:95], v[152:155], v[180:183], v[80:95]
	ds_read_b128 v[152:155], v248 offset:33280
	s_waitcnt lgkmcnt(3)
	v_mfma_f32_32x32x16_bf16 v[64:79], v[156:159], v[180:183], v[64:79]
	ds_read_b128 v[156:159], v248 offset:41472
	s_waitcnt lgkmcnt(3)
	v_mfma_f32_32x32x16_bf16 v[48:63], v[144:147], v[180:183], v[48:63]
	ds_read_b128 v[144:147], v133 offset:512
	s_waitcnt lgkmcnt(3)
	v_mfma_f32_32x32x16_bf16 v[32:47], v[148:151], v[180:183], v[32:47]
	ds_read_b128 v[148:151], v133 offset:8704
	s_waitcnt lgkmcnt(3)
	v_mfma_f32_32x32x16_bf16 v[16:31], v[152:155], v[180:183], v[16:31]
	ds_read_b128 v[152:155], v133 offset:33280
	s_waitcnt lgkmcnt(3)
	v_mfma_f32_32x32x16_bf16 v[0:15], v[156:159], v[180:183], v[0:15]
	ds_read_b128 v[156:159], v133 offset:41472
	s_waitcnt vmcnt(12) lgkmcnt(3)
	v_mfma_f32_32x32x16_bf16 v[112:127], v[144:147], v[184:187], v[112:127]
	ds_read_b128 v[144:147], v249 offset:512
	s_waitcnt lgkmcnt(3)
	v_mfma_f32_32x32x16_bf16 v[96:111], v[148:151], v[184:187], v[96:111]
	ds_read_b128 v[148:151], v249 offset:8704
	s_waitcnt lgkmcnt(3)
	v_mfma_f32_32x32x16_bf16 v[80:95], v[152:155], v[184:187], v[80:95]
	ds_read_b128 v[152:155], v249 offset:33280
	s_waitcnt lgkmcnt(3)
	v_mfma_f32_32x32x16_bf16 v[64:79], v[156:159], v[184:187], v[64:79]
	ds_read_b128 v[156:159], v249 offset:41472
	s_waitcnt lgkmcnt(3)
	v_mfma_f32_32x32x16_bf16 v[48:63], v[144:147], v[184:187], v[48:63]
	ds_read_b128 v[144:147], v129 offset:1024
	s_waitcnt lgkmcnt(3)
	v_mfma_f32_32x32x16_bf16 v[32:47], v[148:151], v[184:187], v[32:47]
	ds_read_b128 v[148:151], v129 offset:9216
	s_waitcnt lgkmcnt(3)
	v_mfma_f32_32x32x16_bf16 v[16:31], v[152:155], v[184:187], v[16:31]
	ds_read_b128 v[152:155], v129 offset:33792
	s_waitcnt lgkmcnt(3)
	v_mfma_f32_32x32x16_bf16 v[0:15], v[156:159], v[184:187], v[0:15]
	ds_read_b128 v[156:159], v129 offset:41984
	s_waitcnt vmcnt(11) lgkmcnt(3)
; #define LDSP(T, p) ((__attribute__((address_space(3))) T*)(p))
; #define MFMA32(a, b, c) __builtin_amdgcn_mfma_f32_32x32x16_bf16((a), (b), (c), 0, 0, 0)
; DI void xattn_unit(const bf16_t* __restrict__ Qg, const bf16_t* __restrict__ Kg, const bf16_t* __restrict__ Vg, bf16_t* __restrict__ Og, lds_t* shm) {
;     ...
; #pragma unroll
;   for (int ss = 0; ss < 16; ++ss) {
;     const int cgl = 2 * ss, img = cgl >> 4;
;     const bf16x8 qv = gld<bf16x8>(Qg + 16 * ss, qoff);
; #pragma unroll
;     for (int t = 0; t < 4; ++t)
; #pragma unroll
;       for (int kb = 0; kb < 2; ++kb) {
;         const bf16x8 kf = *LDSP(const bf16x8, shm + t * 32768 + img * 16384 + kb * 8192 + 512 * ((cgl & 15) >> 2) + ((cgl & 2) ? ka2 : ka0));
;         S[t][kb] = MFMA32(kf, qv, S[t][kb]);
;       }
;   }
	v_mfma_f32_32x32x16_bf16 v[112:127], v[144:147], v[188:191], v[112:127]
	ds_read_b128 v[144:147], v248 offset:1024
	s_waitcnt lgkmcnt(3)
	v_mfma_f32_32x32x16_bf16 v[96:111], v[148:151], v[188:191], v[96:111]
	ds_read_b128 v[148:151], v248 offset:9216
	s_waitcnt lgkmcnt(3)
	v_mfma_f32_32x32x16_bf16 v[80:95], v[152:155], v[188:191], v[80:95]
	ds_read_b128 v[152:155], v248 offset:33792
	s_waitcnt lgkmcnt(3)
	v_mfma_f32_32x32x16_bf16 v[64:79], v[156:159], v[188:191], v[64:79]
	ds_read_b128 v[156:159], v248 offset:41984
	s_waitcnt lgkmcnt(3)
	v_mfma_f32_32x32x16_bf16 v[48:63], v[144:147], v[188:191], v[48:63]
	ds_read_b128 v[144:147], v133 offset:1024
	s_waitcnt lgkmcnt(3)
	v_mfma_f32_32x32x16_bf16 v[32:47], v[148:151], v[188:191], v[32:47]
	ds_read_b128 v[148:151], v133 offset:9216
	s_waitcnt lgkmcnt(3)
	v_mfma_f32_32x32x16_bf16 v[16:31], v[152:155], v[188:191], v[16:31]
	ds_read_b128 v[152:155], v133 offset:33792
	s_waitcnt lgkmcnt(3)
	v_mfma_f32_32x32x16_bf16 v[0:15], v[156:159], v[188:191], v[0:15]
	ds_read_b128 v[156:159], v133 offset:41984
	s_waitcnt vmcnt(10) lgkmcnt(3)
	v_mfma_f32_32x32x16_bf16 v[112:127], v[144:147], v[192:195], v[112:127]
	ds_read_b128 v[144:147], v249 offset:1024
	s_waitcnt lgkmcnt(3)
	v_mfma_f32_32x32x16_bf16 v[96:111], v[148:151], v[192:195], v[96:111]
	ds_read_b128 v[148:151], v249 offset:9216
	s_waitcnt lgkmcnt(3)
	v_mfma_f32_32x32x16_bf16 v[80:95], v[152:155], v[192:195], v[80:95]
	ds_read_b128 v[152:155], v249 offset:33792
	s_waitcnt lgkmcnt(3)
	v_mfma_f32_32x32x16_bf16 v[64:79], v[156:159], v[192:195], v[64:79]
	ds_read_b128 v[156:159], v249 offset:41984
	s_waitcnt lgkmcnt(3)
	v_mfma_f32_32x32x16_bf16 v[48:63], v[144:147], v[192:195], v[48:63]
	ds_read_b128 v[144:147], v129 offset:1536
	s_waitcnt lgkmcnt(3)
	v_mfma_f32_32x32x16_bf16 v[32:47], v[148:151], v[192:195], v[32:47]
	ds_read_b128 v[148:151], v129 offset:9728
	s_waitcnt lgkmcnt(3)
	v_mfma_f32_32x32x16_bf16 v[16:31], v[152:155], v[192:195], v[16:31]
	ds_read_b128 v[152:155], v129 offset:34304
	s_waitcnt lgkmcnt(3)
	v_mfma_f32_32x32x16_bf16 v[0:15], v[156:159], v[192:195], v[0:15]
	ds_read_b128 v[156:159], v129 offset:42496
	s_waitcnt vmcnt(9) lgkmcnt(3)
	v_mfma_f32_32x32x16_bf16 v[112:127], v[144:147], v[196:199], v[112:127]
	ds_read_b128 v[144:147], v248 offset:1536
	s_waitcnt lgkmcnt(3)
	v_mfma_f32_32x32x16_bf16 v[96:111], v[148:151], v[196:199], v[96:111]
	ds_read_b128 v[148:151], v248 offset:9728
	s_waitcnt lgkmcnt(3)
	v_mfma_f32_32x32x16_bf16 v[80:95], v[152:155], v[196:199], v[80:95]
	ds_read_b128 v[152:155], v248 offset:34304
	s_waitcnt lgkmcnt(3)
	v_mfma_f32_32x32x16_bf16 v[64:79], v[156:159], v[196:199], v[64:79]
	ds_read_b128 v[156:159], v248 offset:42496
	s_waitcnt lgkmcnt(3)
	v_mfma_f32_32x32x16_bf16 v[48:63], v[144:147], v[196:199], v[48:63]
	ds_read_b128 v[144:147], v133 offset:1536
	s_waitcnt lgkmcnt(3)
	v_mfma_f32_32x32x16_bf16 v[32:47], v[148:151], v[196:199], v[32:47]
	ds_read_b128 v[148:151], v133 offset:9728
	s_waitcnt lgkmcnt(3)
	v_mfma_f32_32x32x16_bf16 v[16:31], v[152:155], v[196:199], v[16:31]
	ds_read_b128 v[152:155], v133 offset:34304
	s_waitcnt lgkmcnt(3)
	v_mfma_f32_32x32x16_bf16 v[0:15], v[156:159], v[196:199], v[0:15]
	ds_read_b128 v[156:159], v133 offset:42496
	s_waitcnt vmcnt(8) lgkmcnt(3)
	v_mfma_f32_32x32x16_bf16 v[112:127], v[144:147], v[200:203], v[112:127]
	ds_read_b128 v[144:147], v249 offset:1536
	s_waitcnt lgkmcnt(3)
	v_mfma_f32_32x32x16_bf16 v[96:111], v[148:151], v[200:203], v[96:111]
	ds_read_b128 v[148:151], v249 offset:9728
	s_waitcnt lgkmcnt(3)
	v_mfma_f32_32x32x16_bf16 v[80:95], v[152:155], v[200:203], v[80:95]
	ds_read_b128 v[152:155], v249 offset:34304
	s_waitcnt lgkmcnt(3)
	v_mfma_f32_32x32x16_bf16 v[64:79], v[156:159], v[200:203], v[64:79]
	ds_read_b128 v[156:159], v249 offset:42496
	s_waitcnt lgkmcnt(3)
	v_mfma_f32_32x32x16_bf16 v[48:63], v[144:147], v[200:203], v[48:63]
	ds_read_b128 v[144:147], v129 offset:16384
	s_waitcnt lgkmcnt(3)
	v_mfma_f32_32x32x16_bf16 v[32:47], v[148:151], v[200:203], v[32:47]
	ds_read_b128 v[148:151], v129 offset:24576
	s_waitcnt lgkmcnt(3)
	v_mfma_f32_32x32x16_bf16 v[16:31], v[152:155], v[200:203], v[16:31]
	ds_read_b128 v[152:155], v129 offset:49152
	s_waitcnt lgkmcnt(3)
	v_mfma_f32_32x32x16_bf16 v[0:15], v[156:159], v[200:203], v[0:15]
	ds_read_b128 v[156:159], v129 offset:57344
	s_waitcnt vmcnt(7) lgkmcnt(3)
	v_mfma_f32_32x32x16_bf16 v[112:127], v[144:147], v[204:207], v[112:127]
	ds_read_b128 v[144:147], v248 offset:16384
	s_waitcnt lgkmcnt(3)
	v_mfma_f32_32x32x16_bf16 v[96:111], v[148:151], v[204:207], v[96:111]
	ds_read_b128 v[148:151], v248 offset:24576
	s_waitcnt lgkmcnt(3)
	v_mfma_f32_32x32x16_bf16 v[80:95], v[152:155], v[204:207], v[80:95]
	ds_read_b128 v[152:155], v248 offset:49152
	s_waitcnt lgkmcnt(3)
	v_mfma_f32_32x32x16_bf16 v[64:79], v[156:159], v[204:207], v[64:79]
	ds_read_b128 v[156:159], v248 offset:57344
	s_waitcnt lgkmcnt(3)
	v_mfma_f32_32x32x16_bf16 v[48:63], v[144:147], v[204:207], v[48:63]
	ds_read_b128 v[144:147], v133 offset:16384
	s_waitcnt lgkmcnt(3)
	v_mfma_f32_32x32x16_bf16 v[32:47], v[148:151], v[204:207], v[32:47]
	ds_read_b128 v[148:151], v133 offset:24576
	s_waitcnt lgkmcnt(3)
	v_mfma_f32_32x32x16_bf16 v[16:31], v[152:155], v[204:207], v[16:31]
	ds_read_b128 v[152:155], v133 offset:49152
	s_waitcnt lgkmcnt(3)
	v_mfma_f32_32x32x16_bf16 v[0:15], v[156:159], v[204:207], v[0:15]
	ds_read_b128 v[156:159], v133 offset:57344
	s_waitcnt vmcnt(6) lgkmcnt(3)
	v_mfma_f32_32x32x16_bf16 v[112:127], v[144:147], v[208:211], v[112:127]
	ds_read_b128 v[144:147], v249 offset:16384
	s_waitcnt lgkmcnt(3)
; #define LDSP(T, p) ((__attribute__((address_space(3))) T*)(p))
; #define MFMA32(a, b, c) __builtin_amdgcn_mfma_f32_32x32x16_bf16((a), (b), (c), 0, 0, 0)
; DI void xattn_unit(const bf16_t* __restrict__ Qg, const bf16_t* __restrict__ Kg, const bf16_t* __restrict__ Vg, bf16_t* __restrict__ Og, lds_t* shm) {
;     ...
; #pragma unroll
;   for (int ss = 0; ss < 16; ++ss) {
;     const int cgl = 2 * ss, img = cgl >> 4;
;     const bf16x8 qv = gld<bf16x8>(Qg + 16 * ss, qoff);
; #pragma unroll
;     for (int t = 0; t < 4; ++t)
; #pragma unroll
;       for (int kb = 0; kb < 2; ++kb) {
;         const bf16x8 kf = *LDSP(const bf16x8, shm + t * 32768 + img * 16384 + kb * 8192 + 512 * ((cgl & 15) >> 2) + ((cgl & 2) ? ka2 : ka0));
;         S[t][kb] = MFMA32(kf, qv, S[t][kb]);
;       }
;   }
	v_mfma_f32_32x32x16_bf16 v[96:111], v[148:151], v[208:211], v[96:111]
	ds_read_b128 v[148:151], v249 offset:24576
	s_waitcnt lgkmcnt(3)
	v_mfma_f32_32x32x16_bf16 v[80:95], v[152:155], v[208:211], v[80:95]
	ds_read_b128 v[152:155], v249 offset:49152
	s_waitcnt lgkmcnt(3)
	v_mfma_f32_32x32x16_bf16 v[64:79], v[156:159], v[208:211], v[64:79]
	ds_read_b128 v[156:159], v249 offset:57344
	s_waitcnt lgkmcnt(3)
	v_mfma_f32_32x32x16_bf16 v[48:63], v[144:147], v[208:211], v[48:63]
	ds_read_b128 v[144:147], v129 offset:16896
	s_waitcnt lgkmcnt(3)
	v_mfma_f32_32x32x16_bf16 v[32:47], v[148:151], v[208:211], v[32:47]
	ds_read_b128 v[148:151], v129 offset:25088
	s_waitcnt lgkmcnt(3)
	v_mfma_f32_32x32x16_bf16 v[16:31], v[152:155], v[208:211], v[16:31]
	ds_read_b128 v[152:155], v129 offset:49664
	s_waitcnt lgkmcnt(3)
	v_mfma_f32_32x32x16_bf16 v[0:15], v[156:159], v[208:211], v[0:15]
	ds_read_b128 v[156:159], v129 offset:57856
	s_waitcnt vmcnt(5) lgkmcnt(3)
	v_mfma_f32_32x32x16_bf16 v[112:127], v[144:147], v[216:219], v[112:127]
	ds_read_b128 v[144:147], v248 offset:16896
	s_waitcnt lgkmcnt(3)
	v_mfma_f32_32x32x16_bf16 v[96:111], v[148:151], v[216:219], v[96:111]
	ds_read_b128 v[148:151], v248 offset:25088
	s_waitcnt lgkmcnt(3)
	v_mfma_f32_32x32x16_bf16 v[80:95], v[152:155], v[216:219], v[80:95]
	ds_read_b128 v[152:155], v248 offset:49664
	s_waitcnt lgkmcnt(3)
	v_mfma_f32_32x32x16_bf16 v[64:79], v[156:159], v[216:219], v[64:79]
	ds_read_b128 v[156:159], v248 offset:57856
	s_waitcnt lgkmcnt(3)
	v_mfma_f32_32x32x16_bf16 v[48:63], v[144:147], v[216:219], v[48:63]
	ds_read_b128 v[144:147], v133 offset:16896
	s_waitcnt lgkmcnt(3)
	v_mfma_f32_32x32x16_bf16 v[32:47], v[148:151], v[216:219], v[32:47]
	ds_read_b128 v[148:151], v133 offset:25088
	s_waitcnt lgkmcnt(3)
	v_mfma_f32_32x32x16_bf16 v[16:31], v[152:155], v[216:219], v[16:31]
	ds_read_b128 v[152:155], v133 offset:49664
	s_waitcnt lgkmcnt(3)
	v_mfma_f32_32x32x16_bf16 v[0:15], v[156:159], v[216:219], v[0:15]
	ds_read_b128 v[156:159], v133 offset:57856
	s_waitcnt vmcnt(4) lgkmcnt(3)
	v_mfma_f32_32x32x16_bf16 v[112:127], v[144:147], v[220:223], v[112:127]
	ds_read_b128 v[144:147], v249 offset:16896
	s_waitcnt lgkmcnt(3)
	v_mfma_f32_32x32x16_bf16 v[96:111], v[148:151], v[220:223], v[96:111]
	ds_read_b128 v[148:151], v249 offset:25088
	s_waitcnt lgkmcnt(3)
	v_mfma_f32_32x32x16_bf16 v[80:95], v[152:155], v[220:223], v[80:95]
	ds_read_b128 v[152:155], v249 offset:49664
	s_waitcnt lgkmcnt(3)
	v_mfma_f32_32x32x16_bf16 v[64:79], v[156:159], v[220:223], v[64:79]
	ds_read_b128 v[156:159], v249 offset:57856
	s_waitcnt lgkmcnt(3)
	v_mfma_f32_32x32x16_bf16 v[48:63], v[144:147], v[220:223], v[48:63]
	ds_read_b128 v[144:147], v129 offset:17408
	s_waitcnt lgkmcnt(3)
	v_mfma_f32_32x32x16_bf16 v[32:47], v[148:151], v[220:223], v[32:47]
	ds_read_b128 v[148:151], v129 offset:25600
	s_waitcnt lgkmcnt(3)
	v_mfma_f32_32x32x16_bf16 v[16:31], v[152:155], v[220:223], v[16:31]
	ds_read_b128 v[152:155], v129 offset:50176
	s_waitcnt lgkmcnt(3)
	v_mfma_f32_32x32x16_bf16 v[0:15], v[156:159], v[220:223], v[0:15]
	ds_read_b128 v[156:159], v129 offset:58368
	s_waitcnt vmcnt(3) lgkmcnt(3)
	v_mfma_f32_32x32x16_bf16 v[112:127], v[144:147], v[224:227], v[112:127]
	ds_read_b128 v[144:147], v248 offset:17408
	s_waitcnt lgkmcnt(3)
	v_mfma_f32_32x32x16_bf16 v[96:111], v[148:151], v[224:227], v[96:111]
	ds_read_b128 v[148:151], v248 offset:25600
	s_waitcnt lgkmcnt(3)
	v_mfma_f32_32x32x16_bf16 v[80:95], v[152:155], v[224:227], v[80:95]
	ds_read_b128 v[152:155], v248 offset:50176
	s_waitcnt lgkmcnt(3)
	v_mfma_f32_32x32x16_bf16 v[64:79], v[156:159], v[224:227], v[64:79]
	ds_read_b128 v[156:159], v248 offset:58368
	s_waitcnt lgkmcnt(3)
	v_mfma_f32_32x32x16_bf16 v[48:63], v[144:147], v[224:227], v[48:63]
	ds_read_b128 v[144:147], v133 offset:17408
	s_waitcnt lgkmcnt(3)
	v_mfma_f32_32x32x16_bf16 v[32:47], v[148:151], v[224:227], v[32:47]
	ds_read_b128 v[148:151], v133 offset:25600
	s_waitcnt lgkmcnt(3)
	v_mfma_f32_32x32x16_bf16 v[16:31], v[152:155], v[224:227], v[16:31]
	ds_read_b128 v[152:155], v133 offset:50176
	s_waitcnt lgkmcnt(3)
	v_mfma_f32_32x32x16_bf16 v[0:15], v[156:159], v[224:227], v[0:15]
	ds_read_b128 v[156:159], v133 offset:58368
	s_waitcnt vmcnt(2) lgkmcnt(3)
	v_mfma_f32_32x32x16_bf16 v[112:127], v[144:147], v[228:231], v[112:127]
	ds_read_b128 v[144:147], v249 offset:17408
	s_waitcnt lgkmcnt(3)
	v_mfma_f32_32x32x16_bf16 v[96:111], v[148:151], v[228:231], v[96:111]
	ds_read_b128 v[148:151], v249 offset:25600
	s_waitcnt lgkmcnt(3)
	v_mfma_f32_32x32x16_bf16 v[80:95], v[152:155], v[228:231], v[80:95]
	ds_read_b128 v[152:155], v249 offset:50176
	s_waitcnt lgkmcnt(3)
	v_mfma_f32_32x32x16_bf16 v[64:79], v[156:159], v[228:231], v[64:79]
	ds_read_b128 v[156:159], v249 offset:58368
	s_waitcnt lgkmcnt(3)
	v_mfma_f32_32x32x16_bf16 v[48:63], v[144:147], v[228:231], v[48:63]
	ds_read_b128 v[144:147], v129 offset:17920
	s_waitcnt lgkmcnt(3)
	v_mfma_f32_32x32x16_bf16 v[32:47], v[148:151], v[228:231], v[32:47]
	ds_read_b128 v[148:151], v129 offset:26112
	s_waitcnt lgkmcnt(3)
	v_mfma_f32_32x32x16_bf16 v[16:31], v[152:155], v[228:231], v[16:31]
	ds_read_b128 v[152:155], v129 offset:50688
	s_waitcnt lgkmcnt(3)
	v_mfma_f32_32x32x16_bf16 v[0:15], v[156:159], v[228:231], v[0:15]
	ds_read_b128 v[156:159], v129 offset:58880
	s_waitcnt vmcnt(1) lgkmcnt(3)
	v_mfma_f32_32x32x16_bf16 v[112:127], v[144:147], v[232:235], v[112:127]
	ds_read_b128 v[144:147], v248 offset:17920
	s_waitcnt lgkmcnt(3)
	v_mfma_f32_32x32x16_bf16 v[96:111], v[148:151], v[232:235], v[96:111]
	ds_read_b128 v[148:151], v248 offset:26112
	s_waitcnt lgkmcnt(3)
; #define LDSP(T, p) ((__attribute__((address_space(3))) T*)(p))
; #define MFMA32(a, b, c) __builtin_amdgcn_mfma_f32_32x32x16_bf16((a), (b), (c), 0, 0, 0)
; DI void xattn_unit(const bf16_t* __restrict__ Qg, const bf16_t* __restrict__ Kg, const bf16_t* __restrict__ Vg, bf16_t* __restrict__ Og, lds_t* shm) {
;     ...
; #pragma unroll
;   for (int ss = 0; ss < 16; ++ss) {
;     const int cgl = 2 * ss, img = cgl >> 4;
;     const bf16x8 qv = gld<bf16x8>(Qg + 16 * ss, qoff);
; #pragma unroll
;     for (int t = 0; t < 4; ++t)
; #pragma unroll
;       for (int kb = 0; kb < 2; ++kb) {
;         const bf16x8 kf = *LDSP(const bf16x8, shm + t * 32768 + img * 16384 + kb * 8192 + 512 * ((cgl & 15) >> 2) + ((cgl & 2) ? ka2 : ka0));
;         S[t][kb] = MFMA32(kf, qv, S[t][kb]);
;       }
;   }
;   float mx = S[0][0][0];
; #pragma unroll
;   for (int t = 0; t < 4; ++t)
; #pragma unroll
;     for (int kb = 0; kb < 2; ++kb)
; #pragma unroll
;       for (int i = 0; i < 16; ++i) mx = fmaxf(mx, S[t][kb][i]);
;   { const auto sw = __builtin_amdgcn_permlane32_swap(__float_as_uint(mx), __float_as_uint(mx), false, false); mx = fmaxf(__uint_as_float(sw[0]), __uint_as_float(sw[1])); }
;   float rs = 0.f;
;   bf16x8 P[4][2][2];
; #pragma unroll
;   for (int t = 0; t < 4; ++t)
; #pragma unroll
;     for (int kb = 0; kb < 2; ++kb)
; #pragma unroll
;       for (int s2 = 0; s2 < 2; ++s2) {
;         float e[8];
; #pragma unroll
;         for (int j = 0; j < 8; ++j) { e[j] = __builtin_amdgcn_exp2f(S[t][kb][8 * s2 + j] - mx); rs += e[j]; }
	v_mfma_f32_32x32x16_bf16 v[80:95], v[152:155], v[232:235], v[80:95]
	ds_read_b128 v[152:155], v248 offset:50688
	s_waitcnt lgkmcnt(3)
	v_mfma_f32_32x32x16_bf16 v[64:79], v[156:159], v[232:235], v[64:79]
	ds_read_b128 v[156:159], v248 offset:58880
	s_waitcnt lgkmcnt(3)
	v_mfma_f32_32x32x16_bf16 v[48:63], v[144:147], v[232:235], v[48:63]
	ds_read_b128 v[144:147], v133 offset:17920
	s_waitcnt lgkmcnt(3)
	v_mfma_f32_32x32x16_bf16 v[32:47], v[148:151], v[232:235], v[32:47]
	ds_read_b128 v[148:151], v133 offset:26112
	s_waitcnt lgkmcnt(3)
	v_mfma_f32_32x32x16_bf16 v[16:31], v[152:155], v[232:235], v[16:31]
	ds_read_b128 v[152:155], v133 offset:50688
	s_waitcnt lgkmcnt(3)
	v_mfma_f32_32x32x16_bf16 v[0:15], v[156:159], v[232:235], v[0:15]
	ds_read_b128 v[156:159], v133 offset:58880
	s_waitcnt vmcnt(0) lgkmcnt(3)
	v_mfma_f32_32x32x16_bf16 v[112:127], v[144:147], v[236:239], v[112:127]
	ds_read_b128 v[144:147], v249 offset:17920
	s_waitcnt lgkmcnt(3)
	v_mfma_f32_32x32x16_bf16 v[96:111], v[148:151], v[236:239], v[96:111]
	ds_read_b128 v[148:151], v249 offset:26112
	s_waitcnt lgkmcnt(3)
	v_mfma_f32_32x32x16_bf16 v[80:95], v[152:155], v[236:239], v[80:95]
	ds_read_b128 v[152:155], v249 offset:50688
	s_waitcnt lgkmcnt(3)
	v_mfma_f32_32x32x16_bf16 v[64:79], v[156:159], v[236:239], v[64:79]
	ds_read_b128 v[156:159], v249 offset:58880
	s_waitcnt lgkmcnt(3)
	v_mfma_f32_32x32x16_bf16 v[48:63], v[144:147], v[236:239], v[48:63]
	s_waitcnt lgkmcnt(2)
	v_mfma_f32_32x32x16_bf16 v[32:47], v[148:151], v[236:239], v[32:47]
	s_waitcnt lgkmcnt(1)
	v_mfma_f32_32x32x16_bf16 v[16:31], v[152:155], v[236:239], v[16:31]
	s_waitcnt lgkmcnt(0)
	v_mfma_f32_32x32x16_bf16 v[0:15], v[156:159], v[236:239], v[0:15]
	v_max_f32_e32 v128, v113, v113
	v_max_f32_e32 v129, v112, v112
	v_max_f32_e32 v128, v129, v128
	v_max3_f32 v128, v128, v114, v115
	v_max3_f32 v128, v128, v116, v117
	v_max3_f32 v128, v128, v118, v119
	v_max3_f32 v128, v128, v120, v121
	v_max3_f32 v128, v128, v122, v123
	v_max3_f32 v128, v128, v124, v125
	v_max3_f32 v128, v128, v126, v127
	v_max3_f32 v128, v128, v96, v97
	v_max3_f32 v128, v128, v98, v99
	v_max3_f32 v128, v128, v100, v101
	v_max3_f32 v128, v128, v102, v103
	v_max3_f32 v128, v128, v104, v105
	v_max3_f32 v128, v128, v106, v107
	v_max3_f32 v128, v128, v108, v109
	v_max3_f32 v128, v128, v110, v111
	v_max3_f32 v128, v128, v80, v81
	v_max3_f32 v128, v128, v82, v83
	v_max3_f32 v128, v128, v84, v85
	v_max3_f32 v128, v128, v86, v87
	v_max3_f32 v128, v128, v88, v89
	v_max3_f32 v128, v128, v90, v91
	v_max3_f32 v128, v128, v92, v93
	v_max3_f32 v128, v128, v94, v95
	v_max3_f32 v128, v128, v64, v65
	v_max3_f32 v128, v128, v66, v67
	v_max3_f32 v128, v128, v68, v69
	v_max3_f32 v128, v128, v70, v71
	v_max3_f32 v128, v128, v72, v73
	v_max3_f32 v128, v128, v74, v75
	v_max3_f32 v128, v128, v76, v77
	v_max3_f32 v128, v128, v78, v79
	v_max3_f32 v128, v128, v48, v49
	v_max3_f32 v128, v128, v50, v51
	v_max3_f32 v128, v128, v52, v53
	v_max3_f32 v128, v128, v54, v55
	v_max3_f32 v128, v128, v56, v57
	v_max3_f32 v128, v128, v58, v59
	v_max3_f32 v128, v128, v60, v61
	v_max3_f32 v128, v128, v62, v63
	v_max3_f32 v128, v128, v32, v33
	v_max3_f32 v128, v128, v34, v35
	v_max3_f32 v128, v128, v36, v37
	v_max3_f32 v128, v128, v38, v39
	v_max3_f32 v128, v128, v40, v41
	v_max3_f32 v128, v128, v42, v43
	v_max3_f32 v128, v128, v44, v45
	v_max3_f32 v128, v128, v46, v47
	v_max3_f32 v128, v128, v16, v17
	v_max3_f32 v128, v128, v18, v19
	v_max3_f32 v128, v128, v20, v21
	v_max3_f32 v128, v128, v22, v23
	v_max3_f32 v128, v128, v24, v25
	v_max3_f32 v128, v128, v26, v27
	v_max3_f32 v128, v128, v28, v29
	v_max3_f32 v128, v128, v30, v31
	v_max3_f32 v128, v128, v0, v1
	v_max3_f32 v128, v128, v2, v3
	v_max3_f32 v128, v128, v4, v5
	v_max3_f32 v128, v128, v6, v7
	v_max3_f32 v128, v128, v8, v9
	v_max3_f32 v128, v128, v10, v11
	v_max3_f32 v128, v128, v12, v13
	v_max3_f32 v128, v128, v14, v15
	v_mov_b32_e32 v129, v128
	s_nop 1
	v_permlane32_swap_b32_e32 v128, v129
	v_max_f32_e32 v129, v129, v129
	v_max_f32_e32 v128, v128, v128
	v_max_f32_e32 v167, v128, v129
	v_sub_f32_e32 v112, v112, v167
	v_exp_f32_e32 v112, v112
	v_sub_f32_e32 v113, v113, v167
	v_exp_f32_e32 v113, v113
	v_sub_f32_e32 v114, v114, v167
	v_exp_f32_e32 v114, v114
	v_sub_f32_e32 v115, v115, v167
	v_exp_f32_e32 v227, v115
	v_sub_f32_e32 v115, v116, v167
	v_add_f32_e32 v128, 0, v112
	v_exp_f32_e32 v115, v115
	v_sub_f32_e32 v116, v117, v167
	v_add_f32_e32 v128, v113, v128
	v_exp_f32_e32 v116, v116
	v_sub_f32_e32 v117, v118, v167
	v_add_f32_e32 v128, v114, v128
	v_exp_f32_e32 v117, v117
	v_sub_f32_e32 v118, v119, v167
	v_add_f32_e32 v128, v227, v128
	v_exp_f32_e32 v118, v118
	v_sub_f32_e32 v120, v120, v167
	v_add_f32_e32 v128, v115, v128
	v_exp_f32_e32 v217, v120
	v_sub_f32_e32 v120, v121, v167
	v_add_f32_e32 v128, v116, v128
	v_exp_f32_e32 v221, v120
	v_sub_f32_e32 v120, v122, v167
	v_add_f32_e32 v128, v117, v128
	v_exp_f32_e32 v210, v120
	v_sub_f32_e32 v120, v123, v167
	v_add_f32_e32 v119, v118, v128
	v_exp_f32_e32 v218, v120
	v_sub_f32_e32 v120, v124, v167
	v_add_f32_e32 v119, v217, v119
	v_exp_f32_e32 v215, v120
	v_sub_f32_e32 v120, v125, v167
	v_add_f32_e32 v119, v221, v119
	v_exp_f32_e32 v220, v120
	v_sub_f32_e32 v120, v126, v167
	v_add_f32_e32 v119, v210, v119
	v_exp_f32_e32 v208, v120
	v_sub_f32_e32 v120, v127, v167
	v_add_f32_e32 v119, v218, v119
	v_exp_f32_e32 v216, v120
	v_sub_f32_e32 v96, v96, v167
	v_add_f32_e32 v119, v215, v119
	v_exp_f32_e32 v197, v96
	v_sub_f32_e32 v97, v97, v167
	v_add_f32_e32 v119, v220, v119
	v_exp_f32_e32 v201, v97
	v_sub_f32_e32 v97, v98, v167
	v_add_f32_e32 v119, v208, v119
	v_exp_f32_e32 v194, v97
; DI unsigned pk2(float lo, float hi) { bf2_t v = __builtin_convertvector((f32x2){lo, hi}, bf2_t); return __builtin_bit_cast(unsigned, v); }
; DI void xattn_unit(const bf16_t* __restrict__ Qg, const bf16_t* __restrict__ Kg, const bf16_t* __restrict__ Vg, bf16_t* __restrict__ Og, lds_t* shm) {
;     ...
;   float rs = 0.f;
;   bf16x8 P[4][2][2];
; #pragma unroll
;   for (int t = 0; t < 4; ++t)
; #pragma unroll
;     for (int kb = 0; kb < 2; ++kb)
; #pragma unroll
;       for (int s2 = 0; s2 < 2; ++s2) {
;         float e[8];
; #pragma unroll
;         for (int j = 0; j < 8; ++j) { e[j] = __builtin_amdgcn_exp2f(S[t][kb][8 * s2 + j] - mx); rs += e[j]; }
;         u32x4 w; w.x = pk2(e[0], e[1]); w.y = pk2(e[2], e[3]); w.z = pk2(e[4], e[5]); w.w = pk2(e[6], e[7]);
;         P[t][kb][s2] = __builtin_bit_cast(bf16x8, w);
;       }
	v_sub_f32_e32 v97, v99, v167
	v_add_f32_e32 v119, v216, v119
	v_exp_f32_e32 v198, v97
	v_sub_f32_e32 v97, v100, v167
	v_add_f32_e32 v96, v197, v119
	v_exp_f32_e32 v195, v97
	v_sub_f32_e32 v97, v101, v167
	v_add_f32_e32 v96, v201, v96
	v_exp_f32_e32 v199, v97
	v_sub_f32_e32 v97, v102, v167
	v_add_f32_e32 v96, v194, v96
	v_exp_f32_e32 v191, v97
	v_sub_f32_e32 v97, v103, v167
	v_add_f32_e32 v96, v198, v96
	v_exp_f32_e32 v193, v97
	v_sub_f32_e32 v97, v104, v167
	v_add_f32_e32 v96, v195, v96
	v_exp_f32_e32 v179, v97
	v_sub_f32_e32 v97, v105, v167
	v_add_f32_e32 v96, v199, v96
	v_exp_f32_e32 v183, v97
	v_sub_f32_e32 v97, v106, v167
	v_add_f32_e32 v96, v191, v96
	v_exp_f32_e32 v177, v97
	v_sub_f32_e32 v97, v107, v167
	v_add_f32_e32 v96, v193, v96
	v_exp_f32_e32 v180, v97
	v_sub_f32_e32 v97, v108, v167
	v_add_f32_e32 v96, v179, v96
	v_exp_f32_e32 v178, v97
	v_sub_f32_e32 v97, v109, v167
	v_add_f32_e32 v96, v183, v96
	v_exp_f32_e32 v181, v97
	v_sub_f32_e32 v97, v110, v167
	v_add_f32_e32 v96, v177, v96
	v_exp_f32_e32 v174, v97
	v_sub_f32_e32 v97, v111, v167
	v_add_f32_e32 v96, v180, v96
	v_exp_f32_e32 v176, v97
	v_sub_f32_e32 v80, v80, v167
	v_add_f32_e32 v96, v178, v96
	v_exp_f32_e32 v80, v80
	v_sub_f32_e32 v81, v81, v167
	v_add_f32_e32 v96, v181, v96
	v_exp_f32_e32 v81, v81
	v_sub_f32_e32 v82, v82, v167
	v_add_f32_e32 v96, v174, v96
	v_exp_f32_e32 v82, v82
	v_sub_f32_e32 v83, v83, v167
	v_add_f32_e32 v96, v176, v96
	v_exp_f32_e32 v83, v83
	v_sub_f32_e32 v84, v84, v167
	v_add_f32_e32 v96, v80, v96
	v_exp_f32_e32 v84, v84
	v_sub_f32_e32 v85, v85, v167
	v_add_f32_e32 v96, v81, v96
	v_exp_f32_e32 v85, v85
	v_sub_f32_e32 v86, v86, v167
	v_add_f32_e32 v96, v82, v96
	v_exp_f32_e32 v86, v86
	v_sub_f32_e32 v87, v87, v167
	v_add_f32_e32 v96, v83, v96
	v_exp_f32_e32 v87, v87
	v_cvt_pk_bf16_f32 v128, v80, v81
	v_sub_f32_e32 v80, v88, v167
	v_add_f32_e32 v96, v84, v96
	v_cvt_pk_bf16_f32 v129, v82, v83
	v_exp_f32_e32 v80, v80
	v_sub_f32_e32 v82, v89, v167
	v_add_f32_e32 v96, v85, v96
	v_exp_f32_e32 v82, v82
	v_sub_f32_e32 v83, v90, v167
	v_add_f32_e32 v96, v86, v96
	v_cvt_pk_bf16_f32 v130, v84, v85
	v_exp_f32_e32 v83, v83
	v_sub_f32_e32 v84, v91, v167
	v_add_f32_e32 v96, v87, v96
	v_exp_f32_e32 v84, v84
	v_sub_f32_e32 v85, v92, v167
	v_cvt_pk_bf16_f32 v131, v86, v87
	v_add_f32_e32 v81, v80, v96
	v_exp_f32_e32 v85, v85
	v_sub_f32_e32 v86, v93, v167
	v_add_f32_e32 v81, v82, v81
	v_exp_f32_e32 v86, v86
	v_sub_f32_e32 v87, v94, v167
	v_add_f32_e32 v81, v83, v81
	v_exp_f32_e32 v87, v87
	v_sub_f32_e32 v88, v95, v167
	v_add_f32_e32 v81, v84, v81
	v_exp_f32_e32 v88, v88
	v_sub_f32_e32 v64, v64, v167
	v_add_f32_e32 v81, v85, v81
	v_exp_f32_e32 v64, v64
	v_sub_f32_e32 v65, v65, v167
	v_add_f32_e32 v81, v86, v81
	v_exp_f32_e32 v65, v65
	v_sub_f32_e32 v66, v66, v167
	v_add_f32_e32 v81, v87, v81
	v_exp_f32_e32 v66, v66
	v_sub_f32_e32 v67, v67, v167
	v_add_f32_e32 v81, v88, v81
	v_exp_f32_e32 v67, v67
	v_sub_f32_e32 v68, v68, v167
	v_cvt_pk_bf16_f32 v132, v80, v82
	v_add_f32_e32 v80, v64, v81
	v_exp_f32_e32 v68, v68
	v_sub_f32_e32 v69, v69, v167
	v_add_f32_e32 v80, v65, v80
	v_exp_f32_e32 v69, v69
	v_sub_f32_e32 v70, v70, v167
	v_add_f32_e32 v80, v66, v80
	v_exp_f32_e32 v70, v70
	v_sub_f32_e32 v71, v71, v167
	v_add_f32_e32 v80, v67, v80
	v_exp_f32_e32 v71, v71
	v_cvt_pk_bf16_f32 v136, v64, v65
	v_sub_f32_e32 v64, v72, v167
	v_add_f32_e32 v80, v68, v80
	v_cvt_pk_bf16_f32 v137, v66, v67
	v_exp_f32_e32 v64, v64
	v_sub_f32_e32 v66, v73, v167
	v_add_f32_e32 v80, v69, v80
	v_exp_f32_e32 v66, v66
	v_sub_f32_e32 v67, v74, v167
	v_add_f32_e32 v80, v70, v80
	v_cvt_pk_bf16_f32 v138, v68, v69
	v_exp_f32_e32 v67, v67
	v_sub_f32_e32 v68, v75, v167
	v_add_f32_e32 v80, v71, v80
	v_exp_f32_e32 v68, v68
	v_sub_f32_e32 v69, v76, v167
	v_cvt_pk_bf16_f32 v139, v70, v71
	v_add_f32_e32 v65, v64, v80
	v_exp_f32_e32 v69, v69
	v_sub_f32_e32 v70, v77, v167
	v_add_f32_e32 v65, v66, v65
	v_exp_f32_e32 v70, v70
	v_sub_f32_e32 v71, v78, v167
	v_add_f32_e32 v65, v67, v65
	v_exp_f32_e32 v71, v71
	v_sub_f32_e32 v72, v79, v167
	v_add_f32_e32 v65, v68, v65
	v_exp_f32_e32 v72, v72
	v_sub_f32_e32 v48, v48, v167
	v_add_f32_e32 v65, v69, v65
	v_exp_f32_e32 v48, v48
	v_sub_f32_e32 v49, v49, v167
	v_add_f32_e32 v65, v70, v65
	v_exp_f32_e32 v49, v49
	v_sub_f32_e32 v50, v50, v167
	v_add_f32_e32 v65, v71, v65
	v_exp_f32_e32 v50, v50
	v_sub_f32_e32 v51, v51, v167
	v_add_f32_e32 v65, v72, v65
	v_exp_f32_e32 v51, v51
	v_sub_f32_e32 v52, v52, v167
	v_cvt_pk_bf16_f32 v156, v64, v66
	v_add_f32_e32 v64, v48, v65
	v_exp_f32_e32 v52, v52
	v_sub_f32_e32 v53, v53, v167
	v_add_f32_e32 v64, v49, v64
	v_exp_f32_e32 v53, v53
	v_sub_f32_e32 v54, v54, v167
	v_add_f32_e32 v64, v50, v64
	v_exp_f32_e32 v54, v54
	v_sub_f32_e32 v55, v55, v167
	v_add_f32_e32 v64, v51, v64
	v_exp_f32_e32 v55, v55
	v_cvt_pk_bf16_f32 v152, v48, v49
	v_sub_f32_e32 v48, v56, v167
	v_add_f32_e32 v64, v52, v64
	v_cvt_pk_bf16_f32 v153, v50, v51
	v_exp_f32_e32 v48, v48
	v_sub_f32_e32 v50, v57, v167
	v_add_f32_e32 v64, v53, v64
	v_exp_f32_e32 v50, v50
	v_sub_f32_e32 v51, v58, v167
	v_add_f32_e32 v64, v54, v64
	v_cvt_pk_bf16_f32 v154, v52, v53
	v_exp_f32_e32 v51, v51
	v_sub_f32_e32 v52, v59, v167
	v_add_f32_e32 v64, v55, v64
	v_exp_f32_e32 v52, v52
	v_sub_f32_e32 v53, v60, v167
	v_cvt_pk_bf16_f32 v155, v54, v55
	v_add_f32_e32 v49, v48, v64
	v_exp_f32_e32 v53, v53
	v_sub_f32_e32 v54, v61, v167
	v_add_f32_e32 v49, v50, v49
	v_exp_f32_e32 v54, v54
	v_sub_f32_e32 v55, v62, v167
	v_add_f32_e32 v49, v51, v49
	v_exp_f32_e32 v55, v55
	v_sub_f32_e32 v56, v63, v167
	v_add_f32_e32 v49, v52, v49
	v_exp_f32_e32 v56, v56
	v_sub_f32_e32 v32, v32, v167
	v_add_f32_e32 v49, v53, v49
; DI unsigned pk2(float lo, float hi) { bf2_t v = __builtin_convertvector((f32x2){lo, hi}, bf2_t); return __builtin_bit_cast(unsigned, v); }
; DI void xattn_unit(const bf16_t* __restrict__ Qg, const bf16_t* __restrict__ Kg, const bf16_t* __restrict__ Vg, bf16_t* __restrict__ Og, lds_t* shm) {
;     ...
;   float rs = 0.f;
;   bf16x8 P[4][2][2];
; #pragma unroll
;   for (int t = 0; t < 4; ++t)
; #pragma unroll
;     for (int kb = 0; kb < 2; ++kb)
; #pragma unroll
;       for (int s2 = 0; s2 < 2; ++s2) {
;         float e[8];
; #pragma unroll
;         for (int j = 0; j < 8; ++j) { e[j] = __builtin_amdgcn_exp2f(S[t][kb][8 * s2 + j] - mx); rs += e[j]; }
;         u32x4 w; w.x = pk2(e[0], e[1]); w.y = pk2(e[2], e[3]); w.z = pk2(e[4], e[5]); w.w = pk2(e[6], e[7]);
;         P[t][kb][s2] = __builtin_bit_cast(bf16x8, w);
;       }
;   const float l = rs + __shfl_xor(rs, 32);
;   __builtin_amdgcn_sched_barrier(0);
;   __syncthreads();
	v_exp_f32_e32 v32, v32
	v_sub_f32_e32 v33, v33, v167
	v_add_f32_e32 v49, v54, v49
	v_exp_f32_e32 v33, v33
	v_sub_f32_e32 v34, v34, v167
	v_add_f32_e32 v49, v55, v49
	v_exp_f32_e32 v34, v34
	v_sub_f32_e32 v35, v35, v167
	v_add_f32_e32 v49, v56, v49
	v_exp_f32_e32 v35, v35
	v_sub_f32_e32 v36, v36, v167
	v_cvt_pk_bf16_f32 v148, v48, v50
	v_add_f32_e32 v48, v32, v49
	v_exp_f32_e32 v36, v36
	v_sub_f32_e32 v37, v37, v167
	v_add_f32_e32 v48, v33, v48
	v_exp_f32_e32 v37, v37
	v_sub_f32_e32 v38, v38, v167
	v_add_f32_e32 v48, v34, v48
	v_exp_f32_e32 v38, v38
	v_sub_f32_e32 v39, v39, v167
	v_add_f32_e32 v48, v35, v48
	v_exp_f32_e32 v39, v39
	v_cvt_pk_bf16_f32 v140, v32, v33
	v_sub_f32_e32 v32, v40, v167
	v_add_f32_e32 v48, v36, v48
	v_cvt_pk_bf16_f32 v141, v34, v35
	v_exp_f32_e32 v32, v32
	v_sub_f32_e32 v34, v41, v167
	v_add_f32_e32 v48, v37, v48
	v_exp_f32_e32 v34, v34
	v_sub_f32_e32 v35, v42, v167
	v_add_f32_e32 v48, v38, v48
	v_cvt_pk_bf16_f32 v142, v36, v37
	v_exp_f32_e32 v35, v35
	v_sub_f32_e32 v36, v43, v167
	v_add_f32_e32 v48, v39, v48
	v_exp_f32_e32 v36, v36
	v_sub_f32_e32 v37, v44, v167
	v_cvt_pk_bf16_f32 v143, v38, v39
	v_add_f32_e32 v33, v32, v48
	v_exp_f32_e32 v37, v37
	v_sub_f32_e32 v38, v45, v167
	v_add_f32_e32 v33, v34, v33
	v_exp_f32_e32 v38, v38
	v_sub_f32_e32 v39, v46, v167
	v_add_f32_e32 v33, v35, v33
	v_exp_f32_e32 v39, v39
	v_sub_f32_e32 v40, v47, v167
	v_add_f32_e32 v33, v36, v33
	v_exp_f32_e32 v40, v40
	v_sub_f32_e32 v16, v16, v167
	v_add_f32_e32 v33, v37, v33
	v_exp_f32_e32 v171, v16
	v_sub_f32_e32 v17, v17, v167
	v_add_f32_e32 v33, v38, v33
	v_exp_f32_e32 v172, v17
	v_sub_f32_e32 v17, v18, v167
	v_add_f32_e32 v33, v39, v33
	v_exp_f32_e32 v173, v17
	v_sub_f32_e32 v17, v19, v167
	v_add_f32_e32 v33, v40, v33
	v_exp_f32_e32 v175, v17
	v_sub_f32_e32 v17, v20, v167
	v_add_f32_e32 v16, v171, v33
	v_exp_f32_e32 v182, v17
	v_sub_f32_e32 v17, v21, v167
	v_add_f32_e32 v16, v172, v16
	v_exp_f32_e32 v184, v17
	v_sub_f32_e32 v17, v22, v167
	v_add_f32_e32 v16, v173, v16
	v_exp_f32_e32 v185, v17
	v_sub_f32_e32 v17, v23, v167
	v_add_f32_e32 v16, v175, v16
	v_exp_f32_e32 v186, v17
	v_sub_f32_e32 v17, v24, v167
	v_add_f32_e32 v16, v182, v16
	v_exp_f32_e32 v187, v17
	v_sub_f32_e32 v17, v25, v167
	v_add_f32_e32 v16, v184, v16
	v_exp_f32_e32 v188, v17
	v_sub_f32_e32 v17, v26, v167
	v_add_f32_e32 v16, v185, v16
	v_exp_f32_e32 v189, v17
	v_sub_f32_e32 v17, v27, v167
	v_add_f32_e32 v16, v186, v16
	v_exp_f32_e32 v190, v17
	v_sub_f32_e32 v17, v28, v167
	v_add_f32_e32 v16, v187, v16
	v_exp_f32_e32 v192, v17
	v_sub_f32_e32 v17, v29, v167
	v_add_f32_e32 v16, v188, v16
	v_exp_f32_e32 v196, v17
	v_sub_f32_e32 v17, v30, v167
	v_add_f32_e32 v16, v189, v16
	v_exp_f32_e32 v200, v17
	v_sub_f32_e32 v17, v31, v167
	v_add_f32_e32 v16, v190, v16
	v_exp_f32_e32 v202, v17
	v_sub_f32_e32 v0, v0, v167
	v_add_f32_e32 v16, v192, v16
	v_exp_f32_e32 v203, v0
	v_sub_f32_e32 v1, v1, v167
	v_add_f32_e32 v16, v196, v16
	v_exp_f32_e32 v204, v1
	v_sub_f32_e32 v1, v2, v167
	v_add_f32_e32 v16, v200, v16
	v_exp_f32_e32 v205, v1
	v_sub_f32_e32 v1, v3, v167
	v_add_f32_e32 v16, v202, v16
	v_exp_f32_e32 v206, v1
	v_sub_f32_e32 v1, v4, v167
	v_add_f32_e32 v0, v203, v16
	v_exp_f32_e32 v207, v1
	v_sub_f32_e32 v1, v5, v167
	v_add_f32_e32 v0, v204, v0
	v_exp_f32_e32 v209, v1
	v_sub_f32_e32 v1, v6, v167
	v_add_f32_e32 v0, v205, v0
	v_exp_f32_e32 v211, v1
	v_sub_f32_e32 v1, v7, v167
	v_add_f32_e32 v0, v206, v0
	v_exp_f32_e32 v219, v1
	v_sub_f32_e32 v1, v8, v167
	v_add_f32_e32 v0, v207, v0
	v_exp_f32_e32 v222, v1
	v_sub_f32_e32 v1, v9, v167
	v_add_f32_e32 v0, v209, v0
	v_exp_f32_e32 v223, v1
	v_sub_f32_e32 v1, v10, v167
	v_add_f32_e32 v0, v211, v0
	v_exp_f32_e32 v224, v1
	v_sub_f32_e32 v1, v11, v167
	v_add_f32_e32 v0, v219, v0
	v_exp_f32_e32 v225, v1
	v_sub_f32_e32 v1, v12, v167
	v_add_f32_e32 v0, v222, v0
	v_exp_f32_e32 v226, v1
	v_sub_f32_e32 v1, v13, v167
	v_add_f32_e32 v0, v223, v0
	v_exp_f32_e32 v228, v1
	v_sub_f32_e32 v1, v14, v167
	v_add_f32_e32 v0, v224, v0
	v_exp_f32_e32 v229, v1
	v_sub_f32_e32 v1, v15, v167
	v_add_f32_e32 v0, v225, v0
	v_exp_f32_e32 v230, v1
	v_add_f32_e32 v0, v226, v0
	v_add_f32_e32 v0, v228, v0
	v_add_f32_e32 v0, v229, v0
	v_add_f32_e32 v167, v230, v0
	v_cvt_pk_bf16_f32 v133, v83, v84
	v_cvt_pk_bf16_f32 v134, v85, v86
	v_cvt_pk_bf16_f32 v135, v87, v88
	v_cvt_pk_bf16_f32 v157, v67, v68
	v_cvt_pk_bf16_f32 v158, v69, v70
	v_cvt_pk_bf16_f32 v159, v71, v72
	v_cvt_pk_bf16_f32 v149, v51, v52
	v_cvt_pk_bf16_f32 v150, v53, v54
	v_cvt_pk_bf16_f32 v151, v55, v56
	v_cvt_pk_bf16_f32 v144, v32, v34
	v_cvt_pk_bf16_f32 v145, v35, v36
	v_cvt_pk_bf16_f32 v146, v37, v38
	v_cvt_pk_bf16_f32 v147, v39, v40
	ds_bpermute_b32 v168, v213, v167
	s_waitcnt lgkmcnt(0)
	s_barrier
; #define MFMA32(a, b, c) __builtin_amdgcn_mfma_f32_32x32x16_bf16((a), (b), (c), 0, 0, 0)
; DI void xattn_unit(const bf16_t* __restrict__ Qg, const bf16_t* __restrict__ Kg, const bf16_t* __restrict__ Vg, bf16_t* __restrict__ Og, lds_t* shm) {
;     ...
; #pragma unroll
;   for (int t = 1; t < 4; ++t) issue_tile(Vg, t, t * 32768);
;   f32x16 O[NC];
; #pragma unroll
;   for (int c = 0; c < NC; ++c)
; #pragma unroll
;     for (int i = 0; i < 16; ++i) O[c][i] = 0.f;
; #pragma unroll
;   for (int t = 0; t < 4; ++t) {
;     if (t == 1) { __builtin_amdgcn_sched_barrier(0); asm volatile("s_waitcnt vmcnt(0)" ::: "memory"); __syncthreads(); __builtin_amdgcn_sched_barrier(0); }
;     const unsigned vbase = (t == 0) ? 131072u : (unsigned)t * 32768u;
; #pragma unroll
;     for (int ks = 0; ks < 4; ++ks)
; #pragma unroll
;       for (int c = 0; c < NC; ++c) {
;         const unsigned vo = vbase + (c >> 2) * 16384 + 512 * (c & 3) + 4096 * ks;
;         const bf16x8 vf = tr_pair(shm + vo + va0, shm + vo + 2048 + va1);
;         O[c] = MFMA32(vf, P[t][ks >> 1][ks & 1], O[c]);
;       }
	s_add_u32 s38, s36, 0x40800
	s_mov_b32 m0, s67
	s_addc_u32 s39, s37, 0
	global_load_lds_dwordx4 v160, s[38:39]
	s_mov_b32 m0, s0
	v_add_u32_e32 v2, s14, v170
	global_load_lds_dwordx4 v162, s[38:39]
	s_add_u32 s38, s36, 0x40900
	s_addc_u32 s39, s37, 0
	s_mov_b32 m0, s1
	s_add_u32 s0, s36, 0x80800
	global_load_lds_dwordx4 v160, s[38:39]
	s_mov_b32 m0, vcc_lo
	s_addc_u32 s1, s37, 0
	global_load_lds_dwordx4 v162, s[38:39]
	s_mov_b32 m0, vcc_hi
	v_cvt_pk_bf16_f32 v0, v112, v113
	global_load_lds_dwordx4 v160, s[0:1]
	s_mov_b32 m0, s28
	v_cvt_pk_bf16_f32 v1, v114, v227
	global_load_lds_dwordx4 v162, s[0:1]
	s_add_u32 s0, s36, 0x80900
	s_addc_u32 s1, s37, 0
	s_mov_b32 m0, s29
	v_cvt_pk_bf16_f32 v232, v217, v221
	global_load_lds_dwordx4 v160, s[0:1]
	s_mov_b32 m0, s68
	v_cvt_pk_bf16_f32 v233, v210, v218
	global_load_lds_dwordx4 v162, s[0:1]
	s_add_u32 s0, s36, 0xc0800
	s_addc_u32 s1, s37, 0
	s_mov_b32 m0, s69
	v_cvt_pk_bf16_f32 v234, v215, v220
	global_load_lds_dwordx4 v160, s[0:1]
	s_mov_b32 m0, s76
	v_cvt_pk_bf16_f32 v235, v208, v216
	global_load_lds_dwordx4 v162, s[0:1]
	s_add_u32 s0, s36, 0xc0900
	s_addc_u32 s1, s37, 0
	s_mov_b32 m0, s77
	s_nop 0
	global_load_lds_dwordx4 v160, s[0:1]
	s_mov_b32 m0, s78
	v_and_b32_e32 v160, 8, v169
	global_load_lds_dwordx4 v162, s[0:1]
	v_readlane_b32 s0, v254, 14
	v_add3_u32 v2, v2, v166, v160
	s_nop 0
	v_add_u32_e32 v3, s0, v170
	v_add3_u32 v3, v3, v165, v160
	ds_read_b64_tr_b16 v[4:5], v2
	ds_read_b64_tr_b16 v[6:7], v3
	v_readlane_b32 s0, v254, 25
	v_cvt_pk_bf16_f32 v2, v115, v116
	v_cvt_pk_bf16_f32 v3, v117, v118
	v_add_u32_e32 v8, s0, v170
	v_readlane_b32 s0, v254, 26
	v_add3_u32 v8, v8, v166, v160
	s_waitcnt lgkmcnt(0)
	v_mfma_f32_32x32x16_bf16 v[112:127], v[4:7], v[0:3], 0
	v_add_u32_e32 v9, s0, v170
	v_readlane_b32 s0, v254, 27
	v_add3_u32 v10, v9, v165, v160
	ds_read_b64_tr_b16 v[8:9], v8
	ds_read_b64_tr_b16 v[10:11], v10
	v_add_u32_e32 v4, s0, v170
	v_readlane_b32 s0, v254, 28
	v_add3_u32 v4, v4, v166, v160
	s_waitcnt lgkmcnt(0)
	v_mfma_f32_32x32x16_bf16 v[96:111], v[8:11], v[0:3], 0
	v_add_u32_e32 v5, s0, v170
	v_add3_u32 v6, v5, v165, v160
	ds_read_b64_tr_b16 v[4:5], v4
	ds_read_b64_tr_b16 v[6:7], v6
	v_readlane_b32 s0, v254, 29
	s_nop 1
	v_add_u32_e32 v8, s0, v170
	v_readlane_b32 s0, v254, 30
	v_add3_u32 v8, v8, v166, v160
	s_waitcnt lgkmcnt(0)
	v_mfma_f32_32x32x16_bf16 v[80:95], v[4:7], v[0:3], 0
	v_add_u32_e32 v9, s0, v170
	v_readlane_b32 s0, v254, 31
	v_add3_u32 v10, v9, v165, v160
	ds_read_b64_tr_b16 v[8:9], v8
	ds_read_b64_tr_b16 v[10:11], v10
	v_add_u32_e32 v4, s0, v170
	v_readlane_b32 s0, v254, 32
	v_add3_u32 v4, v4, v166, v160
	s_waitcnt lgkmcnt(0)
	v_mfma_f32_32x32x16_bf16 v[64:79], v[8:11], v[0:3], 0
	v_add_u32_e32 v5, s0, v170
	v_add3_u32 v6, v5, v165, v160
	ds_read_b64_tr_b16 v[4:5], v4
	ds_read_b64_tr_b16 v[6:7], v6
	v_readlane_b32 s0, v254, 33
	s_nop 1
	v_add_u32_e32 v8, s0, v170
	v_readlane_b32 s0, v254, 34
	v_add3_u32 v8, v8, v166, v160
	s_waitcnt lgkmcnt(0)
	v_mfma_f32_32x32x16_bf16 v[48:63], v[4:7], v[0:3], 0
	v_add_u32_e32 v9, s0, v170
	v_readlane_b32 s0, v254, 35
	v_add3_u32 v10, v9, v165, v160
	ds_read_b64_tr_b16 v[8:9], v8
	ds_read_b64_tr_b16 v[10:11], v10
	v_add_u32_e32 v4, s0, v170
	v_readlane_b32 s0, v254, 36
	v_add3_u32 v4, v4, v166, v160
	s_waitcnt lgkmcnt(0)
	v_mfma_f32_32x32x16_bf16 v[32:47], v[8:11], v[0:3], 0
	v_add_u32_e32 v5, s0, v170
	v_add3_u32 v6, v5, v165, v160
	ds_read_b64_tr_b16 v[4:5], v4
	ds_read_b64_tr_b16 v[6:7], v6
	v_readlane_b32 s0, v254, 37
	s_nop 1
	v_add_u32_e32 v8, s0, v170
	v_readlane_b32 s0, v254, 38
	s_waitcnt lgkmcnt(0)
	v_mfma_f32_32x32x16_bf16 v[16:31], v[4:7], v[0:3], 0
	v_add3_u32 v8, v8, v166, v160
	v_add_u32_e32 v9, s0, v170
	v_readlane_b32 s0, v254, 39
	v_add3_u32 v10, v9, v165, v160
	ds_read_b64_tr_b16 v[8:9], v8
	ds_read_b64_tr_b16 v[10:11], v10
	v_add_u32_e32 v4, s0, v170
	v_readlane_b32 s0, v254, 40
	v_add3_u32 v4, v4, v166, v160
	s_nop 0
	v_add_u32_e32 v5, s0, v170
	v_readlane_b32 s0, v254, 41
	v_add3_u32 v5, v5, v165, v160
	ds_read_b64_tr_b16 v[236:237], v4
	ds_read_b64_tr_b16 v[238:239], v5
	v_add_u32_e32 v162, s0, v170
	v_readlane_b32 s0, v254, 42
	v_add3_u32 v162, v162, v166, v160
	s_waitcnt lgkmcnt(0)
	v_mfma_f32_32x32x16_bf16 v[112:127], v[236:239], v[232:235], v[112:127]
	v_add_u32_e32 v169, s0, v170
	v_add3_u32 v169, v169, v165, v160
	ds_read_b64_tr_b16 v[240:241], v162
	ds_read_b64_tr_b16 v[242:243], v169
	v_readlane_b32 s0, v254, 43
	s_nop 1
	v_add_u32_e32 v162, s0, v170
	v_readlane_b32 s0, v254, 44
	v_add3_u32 v162, v162, v166, v160
	s_waitcnt lgkmcnt(0)
	v_mfma_f32_32x32x16_bf16 v[96:111], v[240:243], v[232:235], v[96:111]
	v_add_u32_e32 v169, s0, v170
	v_readlane_b32 s0, v254, 45
	v_add3_u32 v169, v169, v165, v160
	ds_read_b64_tr_b16 v[236:237], v162
	ds_read_b64_tr_b16 v[238:239], v169
	v_add_u32_e32 v162, s0, v170
	v_readlane_b32 s0, v254, 46
	v_add3_u32 v162, v162, v166, v160
	s_waitcnt lgkmcnt(0)
	v_mfma_f32_32x32x16_bf16 v[80:95], v[236:239], v[232:235], v[80:95]
	v_add_u32_e32 v169, s0, v170
	v_add3_u32 v169, v169, v165, v160
	ds_read_b64_tr_b16 v[240:241], v162
	ds_read_b64_tr_b16 v[242:243], v169
	v_readlane_b32 s0, v254, 47
	s_nop 1
	v_add_u32_e32 v162, s0, v170
	v_readlane_b32 s0, v254, 48
	v_add3_u32 v162, v162, v166, v160
	s_waitcnt lgkmcnt(0)
	v_mfma_f32_32x32x16_bf16 v[64:79], v[240:243], v[232:235], v[64:79]
	v_add_u32_e32 v169, s0, v170
	v_readlane_b32 s0, v254, 49
	v_add3_u32 v169, v169, v165, v160
	ds_read_b64_tr_b16 v[236:237], v162
	ds_read_b64_tr_b16 v[238:239], v169
	v_add_u32_e32 v162, s0, v170
	v_readlane_b32 s0, v254, 50
	v_add3_u32 v162, v162, v166, v160
	v_mfma_f32_32x32x16_bf16 v[0:15], v[8:11], v[0:3], 0
	v_add_u32_e32 v169, s0, v170
	v_add3_u32 v169, v169, v165, v160
	ds_read_b64_tr_b16 v[240:241], v162
	ds_read_b64_tr_b16 v[242:243], v169
	v_readlane_b32 s0, v254, 51
	s_nop 1
	v_add_u32_e32 v162, s0, v170
	v_readlane_b32 s0, v254, 52
	v_add3_u32 v162, v162, v166, v160
	s_waitcnt lgkmcnt(0)
; #define MFMA32(a, b, c) __builtin_amdgcn_mfma_f32_32x32x16_bf16((a), (b), (c), 0, 0, 0)
; DI void xattn_unit(const bf16_t* __restrict__ Qg, const bf16_t* __restrict__ Kg, const bf16_t* __restrict__ Vg, bf16_t* __restrict__ Og, lds_t* shm) {
;     ...
; #pragma unroll
;   for (int t = 0; t < 4; ++t) {
;     if (t == 1) { __builtin_amdgcn_sched_barrier(0); asm volatile("s_waitcnt vmcnt(0)" ::: "memory"); __syncthreads(); __builtin_amdgcn_sched_barrier(0); }
;     const unsigned vbase = (t == 0) ? 131072u : (unsigned)t * 32768u;
; #pragma unroll
;     for (int ks = 0; ks < 4; ++ks)
; #pragma unroll
;       for (int c = 0; c < NC; ++c) {
;         const unsigned vo = vbase + (c >> 2) * 16384 + 512 * (c & 3) + 4096 * ks;
;         const bf16x8 vf = tr_pair(shm + vo + va0, shm + vo + 2048 + va1);
;         O[c] = MFMA32(vf, P[t][ks >> 1][ks & 1], O[c]);
;       }
	v_mfma_f32_32x32x16_bf16 v[32:47], v[240:243], v[232:235], v[32:47]
	v_add_u32_e32 v169, s0, v170
	v_readlane_b32 s0, v254, 53
	v_add3_u32 v169, v169, v165, v160
	ds_read_b64_tr_b16 v[244:245], v162
	ds_read_b64_tr_b16 v[246:247], v169
	v_add_u32_e32 v162, s0, v170
	v_readlane_b32 s0, v254, 54
	v_add3_u32 v162, v162, v166, v160
	s_waitcnt lgkmcnt(0)
	v_mfma_f32_32x32x16_bf16 v[16:31], v[244:247], v[232:235], v[16:31]
	v_add_u32_e32 v169, s0, v170
	v_add3_u32 v169, v169, v165, v160
	ds_read_b64_tr_b16 v[240:241], v162
	ds_read_b64_tr_b16 v[242:243], v169
	v_readlane_b32 s0, v254, 55
	s_nop 1
	v_add_u32_e32 v162, s0, v170
	v_readlane_b32 s0, v254, 56
	v_add3_u32 v162, v162, v166, v160
	v_mfma_f32_32x32x16_bf16 v[48:63], v[236:239], v[232:235], v[48:63]
	v_add_u32_e32 v169, s0, v170
	v_readlane_b32 s0, v254, 57
	v_add3_u32 v169, v169, v165, v160
	ds_read_b64_tr_b16 v[244:245], v162
	ds_read_b64_tr_b16 v[246:247], v169
	v_add_u32_e32 v162, s0, v170
	v_readlane_b32 s0, v254, 58
	v_add3_u32 v162, v162, v166, v160
	s_waitcnt lgkmcnt(0)
	v_mfma_f32_32x32x16_bf16 v[0:15], v[240:243], v[232:235], v[0:15]
	v_add_u32_e32 v169, s0, v170
	v_add3_u32 v169, v169, v165, v160
	ds_read_b64_tr_b16 v[232:233], v162
	ds_read_b64_tr_b16 v[234:235], v169
	v_readlane_b32 s0, v254, 59
	v_cvt_pk_bf16_f32 v236, v197, v201
	v_cvt_pk_bf16_f32 v237, v194, v198
	v_add_u32_e32 v162, s0, v170
	v_readlane_b32 s0, v254, 60
	v_cvt_pk_bf16_f32 v238, v195, v199
	v_cvt_pk_bf16_f32 v239, v191, v193
	v_add3_u32 v162, v162, v166, v160
	v_add_u32_e32 v169, s0, v170
	v_readlane_b32 s0, v254, 61
	s_waitcnt lgkmcnt(0)
	v_mfma_f32_32x32x16_bf16 v[96:111], v[232:235], v[236:239], v[96:111]
	v_add3_u32 v169, v169, v165, v160
	ds_read_b64_tr_b16 v[232:233], v162
	ds_read_b64_tr_b16 v[234:235], v169
	v_add_u32_e32 v162, s0, v170
	v_readlane_b32 s0, v254, 62
	v_add3_u32 v162, v162, v166, v160
	s_nop 0
	v_add_u32_e32 v169, s0, v170
	v_add3_u32 v169, v169, v165, v160
	ds_read_b64_tr_b16 v[240:241], v162
	ds_read_b64_tr_b16 v[242:243], v169
	v_readlane_b32 s0, v254, 63
	s_waitcnt lgkmcnt(0)
	v_mfma_f32_32x32x16_bf16 v[80:95], v[232:235], v[236:239], v[80:95]
	v_add_u32_e32 v162, s0, v170
	v_readlane_b32 s0, v255, 0
	v_add3_u32 v162, v162, v166, v160
	s_nop 0
	v_add_u32_e32 v169, s0, v170
	v_readlane_b32 s0, v255, 1
	v_add3_u32 v169, v169, v165, v160
	ds_read_b64_tr_b16 v[232:233], v162
	ds_read_b64_tr_b16 v[234:235], v169
	v_add_u32_e32 v162, s0, v170
	v_readlane_b32 s0, v255, 2
	v_add3_u32 v162, v162, v166, v160
	v_mfma_f32_32x32x16_bf16 v[64:79], v[240:243], v[236:239], v[64:79]
	v_add_u32_e32 v169, s0, v170
	v_add3_u32 v169, v169, v165, v160
	ds_read_b64_tr_b16 v[240:241], v162
	ds_read_b64_tr_b16 v[242:243], v169
	v_readlane_b32 s0, v255, 3
	s_nop 1
	v_add_u32_e32 v162, s0, v170
	v_readlane_b32 s0, v255, 4
	v_add3_u32 v162, v162, v166, v160
	v_mfma_f32_32x32x16_bf16 v[112:127], v[244:247], v[236:239], v[112:127]
	v_add_u32_e32 v169, s0, v170
	v_readlane_b32 s0, v255, 5
	v_add3_u32 v169, v169, v165, v160
	ds_read_b64_tr_b16 v[244:245], v162
	ds_read_b64_tr_b16 v[246:247], v169
	v_add_u32_e32 v162, s0, v170
	v_readlane_b32 s0, v255, 6
	v_add3_u32 v162, v162, v166, v160
	s_waitcnt lgkmcnt(0)
	v_mfma_f32_32x32x16_bf16 v[32:47], v[240:243], v[236:239], v[32:47]
	v_add_u32_e32 v169, s0, v170
	v_add3_u32 v169, v169, v165, v160
	ds_read_b64_tr_b16 v[240:241], v162
	ds_read_b64_tr_b16 v[242:243], v169
	v_readlane_b32 s0, v255, 7
	s_nop 1
	v_add_u32_e32 v162, s0, v170
	v_readlane_b32 s0, v255, 8
	v_add3_u32 v162, v162, v166, v160
	v_mfma_f32_32x32x16_bf16 v[48:63], v[232:235], v[236:239], v[48:63]
	v_add_u32_e32 v169, s0, v170
	v_readlane_b32 s0, v255, 9
	v_cvt_pk_bf16_f32 v232, v179, v183
	v_cvt_pk_bf16_f32 v233, v177, v180
	v_cvt_pk_bf16_f32 v234, v178, v181
	v_add3_u32 v169, v169, v165, v160
	ds_read_b64_tr_b16 v[178:179], v162
	ds_read_b64_tr_b16 v[180:181], v169
	v_add_u32_e32 v162, s0, v170
	v_readlane_b32 s0, v255, 10
	v_add3_u32 v162, v162, v166, v160
	v_mfma_f32_32x32x16_bf16 v[16:31], v[244:247], v[236:239], v[16:31]
	v_add_u32_e32 v169, s0, v170
	v_add3_u32 v169, v169, v165, v160
	v_readlane_b32 s0, v255, 11
	v_cvt_pk_bf16_f32 v235, v174, v176
	s_waitcnt lgkmcnt(0)
	v_mfma_f32_32x32x16_bf16 v[0:15], v[240:243], v[236:239], v[0:15]
	ds_read_b64_tr_b16 v[236:237], v162
	ds_read_b64_tr_b16 v[238:239], v169
	v_add_u32_e32 v162, s0, v170
	v_readlane_b32 s0, v255, 12
	v_add3_u32 v162, v162, v166, v160
	s_nop 0
	v_add_u32_e32 v169, s0, v170
	v_readlane_b32 s0, v255, 13
	v_mfma_f32_32x32x16_bf16 v[112:127], v[178:181], v[232:235], v[112:127]
	v_add3_u32 v169, v169, v165, v160
	ds_read_b64_tr_b16 v[176:177], v162
	ds_read_b64_tr_b16 v[178:179], v169
	v_add_u32_e32 v162, s0, v170
	v_readlane_b32 s0, v255, 14
	v_add3_u32 v162, v162, v166, v160
	s_nop 0
	v_add_u32_e32 v169, s0, v170
	s_waitcnt lgkmcnt(0)
	v_mfma_f32_32x32x16_bf16 v[96:111], v[236:239], v[232:235], v[96:111]
	v_add3_u32 v169, v169, v165, v160
	ds_read_b64_tr_b16 v[236:237], v162
	ds_read_b64_tr_b16 v[238:239], v169
	v_readlane_b32 s0, v255, 15
	s_nop 1
	v_add_u32_e32 v162, s0, v170
	v_readlane_b32 s0, v255, 16
	v_add3_u32 v162, v162, v166, v160
	v_mfma_f32_32x32x16_bf16 v[80:95], v[176:179], v[232:235], v[80:95]
	v_add_u32_e32 v169, s0, v170
	v_readlane_b32 s0, v255, 17
	v_add3_u32 v169, v169, v165, v160
	ds_read_b64_tr_b16 v[176:177], v162
	ds_read_b64_tr_b16 v[178:179], v169
	v_add_u32_e32 v162, s0, v170
	v_readlane_b32 s0, v255, 18
	v_add3_u32 v162, v162, v166, v160
	s_waitcnt lgkmcnt(0)
	v_mfma_f32_32x32x16_bf16 v[64:79], v[236:239], v[232:235], v[64:79]
	v_add_u32_e32 v169, s0, v170
	v_add3_u32 v169, v169, v165, v160
	ds_read_b64_tr_b16 v[236:237], v162
	ds_read_b64_tr_b16 v[238:239], v169
	v_readlane_b32 s0, v255, 19
	s_nop 1
	v_add_u32_e32 v162, s0, v170
	v_readlane_b32 s0, v255, 20
	v_add3_u32 v162, v162, v166, v160
	v_mfma_f32_32x32x16_bf16 v[48:63], v[176:179], v[232:235], v[48:63]
	v_add_u32_e32 v169, s0, v170
	v_readlane_b32 s0, v255, 21
	v_add3_u32 v169, v169, v165, v160
	ds_read_b64_tr_b16 v[176:177], v162
	ds_read_b64_tr_b16 v[178:179], v169
	v_add_u32_e32 v162, s0, v170
	v_readlane_b32 s0, v255, 22
	v_add3_u32 v162, v162, v166, v160
	s_waitcnt lgkmcnt(0)
	v_mfma_f32_32x32x16_bf16 v[32:47], v[236:239], v[232:235], v[32:47]
	v_add_u32_e32 v169, s0, v170
	v_add3_u32 v169, v169, v165, v160
	ds_read_b64_tr_b16 v[236:237], v162
	ds_read_b64_tr_b16 v[238:239], v169
	v_mfma_f32_32x32x16_bf16 v[16:31], v[176:179], v[232:235], v[16:31]
	s_waitcnt lgkmcnt(0)
	v_mfma_f32_32x32x16_bf16 v[0:15], v[236:239], v[232:235], v[0:15]
	s_waitcnt vmcnt(0)
	s_waitcnt vmcnt(0)
	s_barrier
; #define MFMA32(a, b, c) __builtin_amdgcn_mfma_f32_32x32x16_bf16((a), (b), (c), 0, 0, 0)
; DI void xattn_unit(const bf16_t* __restrict__ Qg, const bf16_t* __restrict__ Kg, const bf16_t* __restrict__ Vg, bf16_t* __restrict__ Og, lds_t* shm) {
;     ...
; #pragma unroll
;   for (int t = 0; t < 4; ++t) {
;     if (t == 1) { __builtin_amdgcn_sched_barrier(0); asm volatile("s_waitcnt vmcnt(0)" ::: "memory"); __syncthreads(); __builtin_amdgcn_sched_barrier(0); }
;     const unsigned vbase = (t == 0) ? 131072u : (unsigned)t * 32768u;
; #pragma unroll
;     for (int ks = 0; ks < 4; ++ks)
; #pragma unroll
;       for (int c = 0; c < NC; ++c) {
;         const unsigned vo = vbase + (c >> 2) * 16384 + 512 * (c & 3) + 4096 * ks;
;         const bf16x8 vf = tr_pair(shm + vo + va0, shm + vo + 2048 + va1);
;         O[c] = MFMA32(vf, P[t][ks >> 1][ks & 1], O[c]);
;       }
	v_add_u32_e32 v162, 0, v170
	v_add3_u32 v169, v162, v166, v160
	v_add3_u32 v162, v162, v165, v160
	ds_read_b64_tr_b16 v[232:233], v169 offset:32768
	ds_read_b64_tr_b16 v[234:235], v162 offset:34816
	s_add_i32 s0, 0, 0x10000
	s_add_i32 s2, s2, 1
	v_readlane_b32 s68, v254, 0
	s_nop 1
	ds_read_b64_tr_b16 v[236:237], v169 offset:33280
	ds_read_b64_tr_b16 v[238:239], v162 offset:35328
	ds_read_b64_tr_b16 v[240:241], v169 offset:33792
	ds_read_b64_tr_b16 v[242:243], v162 offset:35840
	s_waitcnt lgkmcnt(4)
	v_mfma_f32_32x32x16_bf16 v[112:127], v[232:235], v[128:131], v[112:127]
	ds_read_b64_tr_b16 v[232:233], v169 offset:34304
	ds_read_b64_tr_b16 v[234:235], v162 offset:36352
	s_waitcnt lgkmcnt(4)
	v_mfma_f32_32x32x16_bf16 v[96:111], v[236:239], v[128:131], v[96:111]
	ds_read_b64_tr_b16 v[236:237], v169 offset:49152
	ds_read_b64_tr_b16 v[238:239], v162 offset:51200
	s_waitcnt lgkmcnt(4)
	v_mfma_f32_32x32x16_bf16 v[80:95], v[240:243], v[128:131], v[80:95]
	ds_read_b64_tr_b16 v[240:241], v169 offset:49664
	ds_read_b64_tr_b16 v[242:243], v162 offset:51712
	s_waitcnt lgkmcnt(4)
	v_mfma_f32_32x32x16_bf16 v[64:79], v[232:235], v[128:131], v[64:79]
	ds_read_b64_tr_b16 v[232:233], v169 offset:50176
	ds_read_b64_tr_b16 v[234:235], v162 offset:52224
	s_waitcnt lgkmcnt(4)
	v_mfma_f32_32x32x16_bf16 v[48:63], v[236:239], v[128:131], v[48:63]
	ds_read_b64_tr_b16 v[236:237], v169 offset:50688
	ds_read_b64_tr_b16 v[238:239], v162 offset:52736
	s_waitcnt lgkmcnt(4)
	v_mfma_f32_32x32x16_bf16 v[32:47], v[240:243], v[128:131], v[32:47]
	ds_read_b64_tr_b16 v[240:241], v169 offset:36864
	ds_read_b64_tr_b16 v[242:243], v162 offset:38912
	s_waitcnt lgkmcnt(4)
	v_mfma_f32_32x32x16_bf16 v[16:31], v[232:235], v[128:131], v[16:31]
	ds_read_b64_tr_b16 v[232:233], v169 offset:37376
	ds_read_b64_tr_b16 v[234:235], v162 offset:39424
	s_waitcnt lgkmcnt(4)
	v_mfma_f32_32x32x16_bf16 v[0:15], v[236:239], v[128:131], v[0:15]
	ds_read_b64_tr_b16 v[236:237], v169 offset:37888
	ds_read_b64_tr_b16 v[238:239], v162 offset:39936
	s_waitcnt lgkmcnt(4)
	v_mfma_f32_32x32x16_bf16 v[112:127], v[240:243], v[132:135], v[112:127]
	ds_read_b64_tr_b16 v[240:241], v169 offset:38400
	ds_read_b64_tr_b16 v[242:243], v162 offset:40448
	s_waitcnt lgkmcnt(4)
	v_mfma_f32_32x32x16_bf16 v[96:111], v[232:235], v[132:135], v[96:111]
	ds_read_b64_tr_b16 v[232:233], v169 offset:53248
	ds_read_b64_tr_b16 v[234:235], v162 offset:55296
	s_waitcnt lgkmcnt(4)
	v_mfma_f32_32x32x16_bf16 v[80:95], v[236:239], v[132:135], v[80:95]
	ds_read_b64_tr_b16 v[236:237], v169 offset:53760
	ds_read_b64_tr_b16 v[238:239], v162 offset:55808
	s_waitcnt lgkmcnt(4)
	v_mfma_f32_32x32x16_bf16 v[64:79], v[240:243], v[132:135], v[64:79]
	ds_read_b64_tr_b16 v[240:241], v169 offset:54272
	ds_read_b64_tr_b16 v[242:243], v162 offset:56320
	s_waitcnt lgkmcnt(4)
	v_mfma_f32_32x32x16_bf16 v[48:63], v[232:235], v[132:135], v[48:63]
	ds_read_b64_tr_b16 v[232:233], v169 offset:54784
	ds_read_b64_tr_b16 v[234:235], v162 offset:56832
	s_waitcnt lgkmcnt(4)
	v_mfma_f32_32x32x16_bf16 v[32:47], v[236:239], v[132:135], v[32:47]
	ds_read_b64_tr_b16 v[236:237], v169 offset:40960
	ds_read_b64_tr_b16 v[238:239], v162 offset:43008
	s_waitcnt lgkmcnt(4)
	v_mfma_f32_32x32x16_bf16 v[16:31], v[240:243], v[132:135], v[16:31]
	ds_read_b64_tr_b16 v[240:241], v169 offset:41472
	ds_read_b64_tr_b16 v[242:243], v162 offset:43520
	s_waitcnt lgkmcnt(4)
	v_mfma_f32_32x32x16_bf16 v[0:15], v[232:235], v[132:135], v[0:15]
	ds_read_b64_tr_b16 v[232:233], v169 offset:41984
	ds_read_b64_tr_b16 v[234:235], v162 offset:44032
	v_cvt_pk_bf16_f32 v132, v203, v204
	v_cvt_pk_bf16_f32 v133, v205, v206
	v_cvt_pk_bf16_f32 v134, v207, v209
	v_cvt_pk_bf16_f32 v135, v211, v219
	s_waitcnt lgkmcnt(4)
	v_mfma_f32_32x32x16_bf16 v[112:127], v[236:239], v[136:139], v[112:127]
	ds_read_b64_tr_b16 v[236:237], v169 offset:42496
	ds_read_b64_tr_b16 v[238:239], v162 offset:44544
	s_waitcnt lgkmcnt(4)
	v_mfma_f32_32x32x16_bf16 v[96:111], v[240:243], v[136:139], v[96:111]
	ds_read_b64_tr_b16 v[240:241], v169 offset:57344
	ds_read_b64_tr_b16 v[242:243], v162 offset:59392
	s_waitcnt lgkmcnt(4)
	v_mfma_f32_32x32x16_bf16 v[80:95], v[232:235], v[136:139], v[80:95]
	ds_read_b64_tr_b16 v[232:233], v169 offset:57856
	ds_read_b64_tr_b16 v[234:235], v162 offset:59904
	s_waitcnt lgkmcnt(4)
	v_mfma_f32_32x32x16_bf16 v[64:79], v[236:239], v[136:139], v[64:79]
	ds_read_b64_tr_b16 v[236:237], v169 offset:58368
	ds_read_b64_tr_b16 v[238:239], v162 offset:60416
	s_waitcnt lgkmcnt(4)
	v_mfma_f32_32x32x16_bf16 v[48:63], v[240:243], v[136:139], v[48:63]
	ds_read_b64_tr_b16 v[240:241], v169 offset:58880
	ds_read_b64_tr_b16 v[242:243], v162 offset:60928
	s_waitcnt lgkmcnt(4)
	v_mfma_f32_32x32x16_bf16 v[32:47], v[232:235], v[136:139], v[32:47]
	ds_read_b64_tr_b16 v[232:233], v169 offset:45056
	ds_read_b64_tr_b16 v[234:235], v162 offset:47104
	s_waitcnt lgkmcnt(4)
	v_mfma_f32_32x32x16_bf16 v[16:31], v[236:239], v[136:139], v[16:31]
	ds_read_b64_tr_b16 v[236:237], v169 offset:45568
	ds_read_b64_tr_b16 v[238:239], v162 offset:47616
	s_waitcnt lgkmcnt(4)
	v_mfma_f32_32x32x16_bf16 v[0:15], v[240:243], v[136:139], v[0:15]
	ds_read_b64_tr_b16 v[240:241], v169 offset:46080
	ds_read_b64_tr_b16 v[242:243], v162 offset:48128
	v_cvt_pk_bf16_f32 v136, v187, v188
	v_cvt_pk_bf16_f32 v137, v189, v190
	v_cvt_pk_bf16_f32 v138, v192, v196
	v_cvt_pk_bf16_f32 v139, v200, v202
	s_waitcnt lgkmcnt(4)
	v_mfma_f32_32x32x16_bf16 v[112:127], v[232:235], v[156:159], v[112:127]
	ds_read_b64_tr_b16 v[232:233], v169 offset:46592
	ds_read_b64_tr_b16 v[234:235], v162 offset:48640
	s_waitcnt lgkmcnt(4)
; #define MFMA32(a, b, c) __builtin_amdgcn_mfma_f32_32x32x16_bf16((a), (b), (c), 0, 0, 0)
; DI void xattn_unit(const bf16_t* __restrict__ Qg, const bf16_t* __restrict__ Kg, const bf16_t* __restrict__ Vg, bf16_t* __restrict__ Og, lds_t* shm) {
;     ...
; #pragma unroll
;   for (int t = 0; t < 4; ++t) {
;     if (t == 1) { __builtin_amdgcn_sched_barrier(0); asm volatile("s_waitcnt vmcnt(0)" ::: "memory"); __syncthreads(); __builtin_amdgcn_sched_barrier(0); }
;     const unsigned vbase = (t == 0) ? 131072u : (unsigned)t * 32768u;
; #pragma unroll
;     for (int ks = 0; ks < 4; ++ks)
; #pragma unroll
;       for (int c = 0; c < NC; ++c) {
;         const unsigned vo = vbase + (c >> 2) * 16384 + 512 * (c & 3) + 4096 * ks;
;         const bf16x8 vf = tr_pair(shm + vo + va0, shm + vo + 2048 + va1);
;         O[c] = MFMA32(vf, P[t][ks >> 1][ks & 1], O[c]);
;       }
	v_mfma_f32_32x32x16_bf16 v[96:111], v[236:239], v[156:159], v[96:111]
	ds_read_b64_tr_b16 v[236:237], v169 offset:61440
	ds_read_b64_tr_b16 v[238:239], v162 offset:63488
	s_waitcnt lgkmcnt(4)
	v_mfma_f32_32x32x16_bf16 v[80:95], v[240:243], v[156:159], v[80:95]
	ds_read_b64_tr_b16 v[240:241], v169 offset:61952
	ds_read_b64_tr_b16 v[242:243], v162 offset:64000
	s_waitcnt lgkmcnt(4)
	v_mfma_f32_32x32x16_bf16 v[64:79], v[232:235], v[156:159], v[64:79]
	ds_read_b64_tr_b16 v[232:233], v169 offset:62464
	ds_read_b64_tr_b16 v[234:235], v162 offset:64512
	s_waitcnt lgkmcnt(4)
	v_mfma_f32_32x32x16_bf16 v[48:63], v[236:239], v[156:159], v[48:63]
	ds_read_b64_tr_b16 v[236:237], v169 offset:62976
	ds_read_b64_tr_b16 v[238:239], v162 offset:65024
	s_waitcnt lgkmcnt(4)
	v_mfma_f32_32x32x16_bf16 v[32:47], v[240:243], v[156:159], v[32:47]
	v_add_u32_e32 v240, s0, v170
	v_readlane_b32 s0, v255, 23
	s_nop 1
	v_add3_u32 v240, v240, v166, v160
	s_nop 0
	v_add_u32_e32 v241, s0, v170
	v_add3_u32 v242, v241, v165, v160
	ds_read_b64_tr_b16 v[240:241], v240
	ds_read_b64_tr_b16 v[242:243], v242
	s_add_i32 s0, 0, 0x10200
	s_waitcnt lgkmcnt(4)
	v_mfma_f32_32x32x16_bf16 v[16:31], v[232:235], v[156:159], v[16:31]
	v_add_u32_e32 v232, s0, v170
	v_readlane_b32 s0, v255, 24
	s_nop 1
	v_add3_u32 v232, v232, v166, v160
	s_nop 0
	v_add_u32_e32 v233, s0, v170
	v_add3_u32 v234, v233, v165, v160
	ds_read_b64_tr_b16 v[232:233], v232
	ds_read_b64_tr_b16 v[234:235], v234
	s_add_i32 s0, 0, 0x10400
	s_waitcnt lgkmcnt(4)
	v_mfma_f32_32x32x16_bf16 v[0:15], v[236:239], v[156:159], v[0:15]
	v_add_u32_e32 v236, s0, v170
	v_readlane_b32 s0, v255, 25
	s_nop 1
	v_add3_u32 v236, v236, v166, v160
	s_nop 0
	v_add_u32_e32 v237, s0, v170
	v_add3_u32 v238, v237, v165, v160
	ds_read_b64_tr_b16 v[236:237], v236
	ds_read_b64_tr_b16 v[238:239], v238
	s_add_i32 s0, 0, 0x10600
	s_waitcnt lgkmcnt(4)
	v_mfma_f32_32x32x16_bf16 v[112:127], v[240:243], v[152:155], v[112:127]
	v_add_u32_e32 v240, s0, v170
	v_readlane_b32 s0, v255, 26
	s_nop 1
	v_add3_u32 v240, v240, v166, v160
	s_nop 0
	v_add_u32_e32 v241, s0, v170
	v_add3_u32 v242, v241, v165, v160
	ds_read_b64_tr_b16 v[240:241], v240
	ds_read_b64_tr_b16 v[242:243], v242
	s_add_i32 s0, 0, 0x14000
	s_waitcnt lgkmcnt(4)
	v_mfma_f32_32x32x16_bf16 v[96:111], v[232:235], v[152:155], v[96:111]
	v_add_u32_e32 v232, s0, v170
	v_readlane_b32 s0, v255, 27
	s_nop 1
	v_add3_u32 v232, v232, v166, v160
	s_nop 0
	v_add_u32_e32 v233, s0, v170
	v_add3_u32 v234, v233, v165, v160
	ds_read_b64_tr_b16 v[232:233], v232
	ds_read_b64_tr_b16 v[234:235], v234
	s_add_i32 s0, 0, 0x14200
	s_waitcnt lgkmcnt(4)
	v_mfma_f32_32x32x16_bf16 v[80:95], v[236:239], v[152:155], v[80:95]
	v_add_u32_e32 v236, s0, v170
	v_readlane_b32 s0, v255, 28
	s_nop 1
	v_add3_u32 v236, v236, v166, v160
	s_nop 0
	v_add_u32_e32 v237, s0, v170
	v_add3_u32 v238, v237, v165, v160
	ds_read_b64_tr_b16 v[236:237], v236
	ds_read_b64_tr_b16 v[238:239], v238
	s_add_i32 s0, 0, 0x14400
	s_waitcnt lgkmcnt(4)
	v_mfma_f32_32x32x16_bf16 v[64:79], v[240:243], v[152:155], v[64:79]
	v_add_u32_e32 v240, s0, v170
	v_readlane_b32 s0, v255, 29
	s_nop 1
	v_add3_u32 v240, v240, v166, v160
	s_nop 0
	v_add_u32_e32 v241, s0, v170
	v_add3_u32 v242, v241, v165, v160
	ds_read_b64_tr_b16 v[240:241], v240
	ds_read_b64_tr_b16 v[242:243], v242
	s_add_i32 s0, 0, 0x14600
	s_waitcnt lgkmcnt(4)
	v_mfma_f32_32x32x16_bf16 v[48:63], v[232:235], v[152:155], v[48:63]
	v_add_u32_e32 v232, s0, v170
	v_readlane_b32 s0, v255, 30
	s_nop 1
	v_add3_u32 v232, v232, v166, v160
	s_nop 0
	v_add_u32_e32 v233, s0, v170
	v_add3_u32 v234, v233, v165, v160
	ds_read_b64_tr_b16 v[232:233], v232
	ds_read_b64_tr_b16 v[234:235], v234
	v_readlane_b32 s0, v255, 31
	s_nop 1
	s_waitcnt lgkmcnt(4)
	v_mfma_f32_32x32x16_bf16 v[32:47], v[236:239], v[152:155], v[32:47]
	v_add_u32_e32 v236, s0, v170
	v_readlane_b32 s0, v255, 32
	s_nop 1
	v_add3_u32 v236, v236, v166, v160
	s_nop 0
	v_add_u32_e32 v237, s0, v170
	v_add3_u32 v238, v237, v165, v160
	ds_read_b64_tr_b16 v[236:237], v236
	ds_read_b64_tr_b16 v[238:239], v238
	v_readlane_b32 s0, v255, 33
	s_nop 1
	s_waitcnt lgkmcnt(4)
	v_mfma_f32_32x32x16_bf16 v[16:31], v[240:243], v[152:155], v[16:31]
	v_add_u32_e32 v240, s0, v170
	v_readlane_b32 s0, v255, 34
	s_nop 1
	v_add3_u32 v240, v240, v166, v160
	s_nop 0
	v_add_u32_e32 v241, s0, v170
	v_add3_u32 v242, v241, v165, v160
	ds_read_b64_tr_b16 v[240:241], v240
	ds_read_b64_tr_b16 v[242:243], v242
	v_readlane_b32 s0, v255, 35
	s_nop 1
	s_waitcnt lgkmcnt(4)
	v_mfma_f32_32x32x16_bf16 v[0:15], v[232:235], v[152:155], v[0:15]
	v_add_u32_e32 v232, s0, v170
	v_readlane_b32 s0, v255, 36
	s_nop 1
	v_add3_u32 v232, v232, v166, v160
	s_nop 0
	v_add_u32_e32 v233, s0, v170
	v_add3_u32 v234, v233, v165, v160
	ds_read_b64_tr_b16 v[232:233], v232
	ds_read_b64_tr_b16 v[234:235], v234
	v_readlane_b32 s0, v255, 37
	s_nop 1
	s_waitcnt lgkmcnt(4)
	v_mfma_f32_32x32x16_bf16 v[112:127], v[236:239], v[148:151], v[112:127]
	v_add_u32_e32 v236, s0, v170
	v_readlane_b32 s0, v255, 38
	s_nop 1
	v_add3_u32 v236, v236, v166, v160
	s_nop 0
	v_add_u32_e32 v237, s0, v170
	v_add3_u32 v238, v237, v165, v160
	ds_read_b64_tr_b16 v[236:237], v236
	ds_read_b64_tr_b16 v[238:239], v238
	v_readlane_b32 s0, v255, 39
	s_nop 1
	s_waitcnt lgkmcnt(4)
	v_mfma_f32_32x32x16_bf16 v[96:111], v[240:243], v[148:151], v[96:111]
	v_add_u32_e32 v240, s0, v170
	v_readlane_b32 s0, v255, 40
	s_nop 1
	v_add3_u32 v240, v240, v166, v160
	s_nop 0
	v_add_u32_e32 v241, s0, v170
	v_add3_u32 v242, v241, v165, v160
	ds_read_b64_tr_b16 v[240:241], v240
	ds_read_b64_tr_b16 v[242:243], v242
	v_readlane_b32 s0, v255, 41
	s_nop 1
	s_waitcnt lgkmcnt(4)
; #define MFMA32(a, b, c) __builtin_amdgcn_mfma_f32_32x32x16_bf16((a), (b), (c), 0, 0, 0)
; DI void xattn_unit(const bf16_t* __restrict__ Qg, const bf16_t* __restrict__ Kg, const bf16_t* __restrict__ Vg, bf16_t* __restrict__ Og, lds_t* shm) {
;     ...
; #pragma unroll
;   for (int t = 0; t < 4; ++t) {
;     if (t == 1) { __builtin_amdgcn_sched_barrier(0); asm volatile("s_waitcnt vmcnt(0)" ::: "memory"); __syncthreads(); __builtin_amdgcn_sched_barrier(0); }
;     const unsigned vbase = (t == 0) ? 131072u : (unsigned)t * 32768u;
; #pragma unroll
;     for (int ks = 0; ks < 4; ++ks)
; #pragma unroll
;       for (int c = 0; c < NC; ++c) {
;         const unsigned vo = vbase + (c >> 2) * 16384 + 512 * (c & 3) + 4096 * ks;
;         const bf16x8 vf = tr_pair(shm + vo + va0, shm + vo + 2048 + va1);
;         O[c] = MFMA32(vf, P[t][ks >> 1][ks & 1], O[c]);
;       }
;   }
	v_mfma_f32_32x32x16_bf16 v[80:95], v[232:235], v[148:151], v[80:95]
	v_add_u32_e32 v232, s0, v170
	v_readlane_b32 s0, v255, 42
	s_nop 1
	v_add3_u32 v232, v232, v166, v160
	s_nop 0
	v_add_u32_e32 v233, s0, v170
	v_add3_u32 v234, v233, v165, v160
	ds_read_b64_tr_b16 v[232:233], v232
	ds_read_b64_tr_b16 v[234:235], v234
	v_readlane_b32 s0, v255, 43
	s_nop 1
	s_waitcnt lgkmcnt(4)
	v_mfma_f32_32x32x16_bf16 v[64:79], v[236:239], v[148:151], v[64:79]
	v_add_u32_e32 v236, s0, v170
	v_readlane_b32 s0, v255, 44
	s_nop 1
	v_add3_u32 v236, v236, v166, v160
	s_nop 0
	v_add_u32_e32 v237, s0, v170
	v_add3_u32 v238, v237, v165, v160
	ds_read_b64_tr_b16 v[236:237], v236
	ds_read_b64_tr_b16 v[238:239], v238
	v_readlane_b32 s0, v255, 45
	s_nop 1
	s_waitcnt lgkmcnt(4)
	v_mfma_f32_32x32x16_bf16 v[48:63], v[240:243], v[148:151], v[48:63]
	v_add_u32_e32 v240, s0, v170
	v_readlane_b32 s0, v255, 46
	s_nop 1
	v_add3_u32 v240, v240, v166, v160
	s_nop 0
	v_add_u32_e32 v241, s0, v170
	v_add3_u32 v242, v241, v165, v160
	ds_read_b64_tr_b16 v[240:241], v240
	ds_read_b64_tr_b16 v[242:243], v242
	s_add_i32 s0, 0, 0x12000
	s_waitcnt lgkmcnt(4)
	v_mfma_f32_32x32x16_bf16 v[32:47], v[232:235], v[148:151], v[32:47]
	v_add_u32_e32 v232, s0, v170
	v_readlane_b32 s0, v255, 47
	s_nop 1
	v_add3_u32 v232, v232, v166, v160
	s_nop 0
	v_add_u32_e32 v233, s0, v170
	v_add3_u32 v234, v233, v165, v160
	ds_read_b64_tr_b16 v[232:233], v232
	ds_read_b64_tr_b16 v[234:235], v234
	s_add_i32 s0, 0, 0x12200
	s_waitcnt lgkmcnt(4)
	v_mfma_f32_32x32x16_bf16 v[16:31], v[236:239], v[148:151], v[16:31]
	v_add_u32_e32 v236, s0, v170
	v_readlane_b32 s0, v255, 48
	s_nop 1
	v_add3_u32 v236, v236, v166, v160
	s_nop 0
	v_add_u32_e32 v237, s0, v170
	v_add3_u32 v238, v237, v165, v160
	ds_read_b64_tr_b16 v[236:237], v236
	ds_read_b64_tr_b16 v[238:239], v238
	s_add_i32 s0, 0, 0x12400
	s_waitcnt lgkmcnt(4)
	v_mfma_f32_32x32x16_bf16 v[0:15], v[240:243], v[148:151], v[0:15]
	v_add_u32_e32 v240, s0, v170
	v_readlane_b32 s0, v255, 49
	s_nop 1
	v_add3_u32 v240, v240, v166, v160
	s_nop 0
	v_add_u32_e32 v241, s0, v170
	v_add3_u32 v242, v241, v165, v160
	ds_read_b64_tr_b16 v[240:241], v240
	ds_read_b64_tr_b16 v[242:243], v242
	s_add_i32 s0, 0, 0x12600
	s_waitcnt lgkmcnt(4)
	v_mfma_f32_32x32x16_bf16 v[112:127], v[232:235], v[140:143], v[112:127]
	v_add_u32_e32 v232, s0, v170
	v_readlane_b32 s0, v255, 50
	s_nop 1
	v_add3_u32 v232, v232, v166, v160
	s_nop 0
	v_add_u32_e32 v233, s0, v170
	v_add3_u32 v234, v233, v165, v160
	ds_read_b64_tr_b16 v[232:233], v232
	ds_read_b64_tr_b16 v[234:235], v234
	s_add_i32 s0, 0, 0x16000
	s_waitcnt lgkmcnt(4)
	v_mfma_f32_32x32x16_bf16 v[96:111], v[236:239], v[140:143], v[96:111]
	v_add_u32_e32 v236, s0, v170
	v_readlane_b32 s0, v255, 51
	s_nop 1
	v_add3_u32 v236, v236, v166, v160
	s_nop 0
	v_add_u32_e32 v237, s0, v170
	v_add3_u32 v238, v237, v165, v160
	ds_read_b64_tr_b16 v[236:237], v236
	ds_read_b64_tr_b16 v[238:239], v238
	s_add_i32 s0, 0, 0x16200
	s_waitcnt lgkmcnt(4)
	v_mfma_f32_32x32x16_bf16 v[80:95], v[240:243], v[140:143], v[80:95]
	v_add_u32_e32 v240, s0, v170
	v_readlane_b32 s0, v255, 52
	s_nop 1
	v_add3_u32 v240, v240, v166, v160
	s_nop 0
	v_add_u32_e32 v241, s0, v170
	v_add3_u32 v242, v241, v165, v160
	ds_read_b64_tr_b16 v[240:241], v240
	ds_read_b64_tr_b16 v[242:243], v242
	s_add_i32 s0, 0, 0x16400
	s_waitcnt lgkmcnt(4)
	v_mfma_f32_32x32x16_bf16 v[64:79], v[232:235], v[140:143], v[64:79]
	v_add_u32_e32 v232, s0, v170
	v_readlane_b32 s0, v255, 53
	s_nop 1
	v_add3_u32 v232, v232, v166, v160
	s_nop 0
	v_add_u32_e32 v233, s0, v170
	v_add3_u32 v234, v233, v165, v160
	ds_read_b64_tr_b16 v[232:233], v232
	ds_read_b64_tr_b16 v[234:235], v234
	s_add_i32 s0, 0, 0x16600
	s_waitcnt lgkmcnt(4)
	v_mfma_f32_32x32x16_bf16 v[48:63], v[236:239], v[140:143], v[48:63]
	v_add_u32_e32 v236, s0, v170
	v_readlane_b32 s0, v255, 54
	s_nop 1
	v_add3_u32 v236, v236, v166, v160
	s_nop 0
	v_add_u32_e32 v237, s0, v170
	v_add3_u32 v238, v237, v165, v160
	ds_read_b64_tr_b16 v[236:237], v236
	ds_read_b64_tr_b16 v[238:239], v238
	v_readlane_b32 s0, v255, 55
	s_nop 1
	s_waitcnt lgkmcnt(4)
	v_mfma_f32_32x32x16_bf16 v[32:47], v[240:243], v[140:143], v[32:47]
	v_add_u32_e32 v240, s0, v170
	v_readlane_b32 s0, v255, 56
	s_nop 1
	v_add3_u32 v240, v240, v166, v160
	v_add_u32_e32 v241, s0, v170
	v_add3_u32 v242, v241, v165, v160
	ds_read_b64_tr_b16 v[240:241], v240
	ds_read_b64_tr_b16 v[242:243], v242
	v_readlane_b32 s0, v255, 57
	s_nop 1
	s_waitcnt lgkmcnt(4)
	v_mfma_f32_32x32x16_bf16 v[16:31], v[232:235], v[140:143], v[16:31]
	v_add_u32_e32 v232, s0, v170
	v_readlane_b32 s0, v255, 58
	s_nop 1
	v_add3_u32 v232, v232, v166, v160
	v_add_u32_e32 v233, s0, v170
	v_add3_u32 v234, v233, v165, v160
	ds_read_b64_tr_b16 v[232:233], v232
	ds_read_b64_tr_b16 v[234:235], v234
	v_readlane_b32 s0, v255, 59
	s_nop 1
	s_waitcnt lgkmcnt(4)
	v_mfma_f32_32x32x16_bf16 v[0:15], v[236:239], v[140:143], v[0:15]
	v_add_u32_e32 v236, s0, v170
	v_readlane_b32 s0, v255, 60
	s_nop 1
	v_add3_u32 v236, v236, v166, v160
	v_add_u32_e32 v237, s0, v170
	v_add3_u32 v238, v237, v165, v160
	ds_read_b64_tr_b16 v[236:237], v236
	ds_read_b64_tr_b16 v[238:239], v238
	v_readlane_b32 s0, v255, 61
	s_nop 1
	v_cvt_pk_bf16_f32 v140, v171, v172
	s_waitcnt lgkmcnt(4)
	v_mfma_f32_32x32x16_bf16 v[112:127], v[240:243], v[144:147], v[112:127]
	v_add_u32_e32 v240, s0, v170
	v_readlane_b32 s0, v255, 62
	s_nop 1
	v_add3_u32 v240, v240, v166, v160
	v_add_u32_e32 v241, s0, v170
	v_add3_u32 v242, v241, v165, v160
	ds_read_b64_tr_b16 v[240:241], v240
	ds_read_b64_tr_b16 v[242:243], v242
	v_cvt_pk_bf16_f32 v141, v173, v175
	s_waitcnt lgkmcnt(4)
; #define MFMA32(a, b, c) __builtin_amdgcn_mfma_f32_32x32x16_bf16((a), (b), (c), 0, 0, 0)
; DI void xattn_unit(const bf16_t* __restrict__ Qg, const bf16_t* __restrict__ Kg, const bf16_t* __restrict__ Vg, bf16_t* __restrict__ Og, lds_t* shm) {
;     ...
; #pragma unroll
;   for (int t = 0; t < 4; ++t) {
;     if (t == 1) { __builtin_amdgcn_sched_barrier(0); asm volatile("s_waitcnt vmcnt(0)" ::: "memory"); __syncthreads(); __builtin_amdgcn_sched_barrier(0); }
;     const unsigned vbase = (t == 0) ? 131072u : (unsigned)t * 32768u;
; #pragma unroll
;     for (int ks = 0; ks < 4; ++ks)
; #pragma unroll
;       for (int c = 0; c < NC; ++c) {
;         const unsigned vo = vbase + (c >> 2) * 16384 + 512 * (c & 3) + 4096 * ks;
;         const bf16x8 vf = tr_pair(shm + vo + va0, shm + vo + 2048 + va1);
;         O[c] = MFMA32(vf, P[t][ks >> 1][ks & 1], O[c]);
;       }
;   }
	v_mfma_f32_32x32x16_bf16 v[96:111], v[232:235], v[144:147], v[96:111]
	v_add_u32_e32 v232, s83, v170
	v_add_u32_e32 v233, s84, v170
	v_add3_u32 v232, v232, v166, v160
	v_add3_u32 v234, v233, v165, v160
	ds_read_b64_tr_b16 v[232:233], v232
	ds_read_b64_tr_b16 v[234:235], v234
	s_add_i32 s0, 0, 0x18000
	v_cvt_pk_bf16_f32 v142, v182, v184
	s_waitcnt lgkmcnt(4)
	v_mfma_f32_32x32x16_bf16 v[80:95], v[236:239], v[144:147], v[80:95]
	v_add_u32_e32 v236, s85, v170
	v_add_u32_e32 v237, s86, v170
	v_add3_u32 v236, v236, v166, v160
	v_add3_u32 v238, v237, v165, v160
	ds_read_b64_tr_b16 v[236:237], v236
	ds_read_b64_tr_b16 v[238:239], v238
	v_cvt_pk_bf16_f32 v143, v185, v186
	s_waitcnt lgkmcnt(4)
	v_mfma_f32_32x32x16_bf16 v[64:79], v[240:243], v[144:147], v[64:79]
	v_add_u32_e32 v240, s87, v170
	v_add_u32_e32 v241, s88, v170
	v_add3_u32 v240, v240, v166, v160
	v_add3_u32 v242, v241, v165, v160
	ds_read_b64_tr_b16 v[240:241], v240
	ds_read_b64_tr_b16 v[242:243], v242
	s_waitcnt lgkmcnt(4)
	v_mfma_f32_32x32x16_bf16 v[48:63], v[232:235], v[144:147], v[48:63]
	v_add_u32_e32 v232, s89, v170
	v_add_u32_e32 v233, s90, v170
	v_add3_u32 v232, v232, v166, v160
	v_add3_u32 v234, v233, v165, v160
	ds_read_b64_tr_b16 v[232:233], v232
	ds_read_b64_tr_b16 v[234:235], v234
	s_waitcnt lgkmcnt(4)
	v_mfma_f32_32x32x16_bf16 v[32:47], v[236:239], v[144:147], v[32:47]
	v_add_u32_e32 v236, s0, v170
	v_add_u32_e32 v237, s91, v170
	v_add3_u32 v236, v236, v166, v160
	v_add3_u32 v238, v237, v165, v160
	ds_read_b64_tr_b16 v[236:237], v236
	ds_read_b64_tr_b16 v[238:239], v238
	s_add_i32 s0, 0, 0x18200
	s_waitcnt lgkmcnt(4)
	v_mfma_f32_32x32x16_bf16 v[16:31], v[240:243], v[144:147], v[16:31]
	v_add_u32_e32 v240, s0, v170
	v_add_u32_e32 v241, s92, v170
	v_add3_u32 v240, v240, v166, v160
	v_add3_u32 v242, v241, v165, v160
	ds_read_b64_tr_b16 v[240:241], v240
	ds_read_b64_tr_b16 v[242:243], v242
	s_add_i32 s0, 0, 0x18400
	s_waitcnt lgkmcnt(4)
	v_mfma_f32_32x32x16_bf16 v[0:15], v[232:235], v[144:147], v[0:15]
	v_add_u32_e32 v232, s0, v170
	v_add_u32_e32 v233, s93, v170
	v_add3_u32 v232, v232, v166, v160
	v_add3_u32 v234, v233, v165, v160
	ds_read_b64_tr_b16 v[232:233], v232
	ds_read_b64_tr_b16 v[234:235], v234
	s_add_i32 s0, 0, 0x18600
	v_cvt_pk_bf16_f32 v128, v222, v223
	s_waitcnt lgkmcnt(4)
	v_mfma_f32_32x32x16_bf16 v[112:127], v[236:239], v[140:143], v[112:127]
	v_add_u32_e32 v236, s0, v170
	v_add_u32_e32 v237, s94, v170
	v_add3_u32 v236, v236, v166, v160
	v_add3_u32 v238, v237, v165, v160
	ds_read_b64_tr_b16 v[236:237], v236
	ds_read_b64_tr_b16 v[238:239], v238
	s_add_i32 s0, 0, 0x1c000
	v_cvt_pk_bf16_f32 v129, v224, v225
	s_waitcnt lgkmcnt(4)
	v_mfma_f32_32x32x16_bf16 v[96:111], v[240:243], v[140:143], v[96:111]
	v_add_u32_e32 v240, s0, v170
	v_add_u32_e32 v241, s95, v170
	v_add3_u32 v240, v240, v166, v160
	v_add3_u32 v242, v241, v165, v160
	ds_read_b64_tr_b16 v[240:241], v240
	ds_read_b64_tr_b16 v[242:243], v242
	s_add_i32 s0, 0, 0x1c200
	v_cvt_pk_bf16_f32 v130, v226, v228
	s_waitcnt lgkmcnt(4)
	v_mfma_f32_32x32x16_bf16 v[80:95], v[232:235], v[140:143], v[80:95]
	v_add_u32_e32 v232, s0, v170
	v_add_u32_e32 v233, s96, v170
	v_add3_u32 v232, v232, v166, v160
	v_add3_u32 v234, v233, v165, v160
	ds_read_b64_tr_b16 v[232:233], v232
	ds_read_b64_tr_b16 v[234:235], v234
	s_add_i32 s0, 0, 0x1c400
	v_cvt_pk_bf16_f32 v131, v229, v230
	s_waitcnt lgkmcnt(4)
	v_mfma_f32_32x32x16_bf16 v[64:79], v[236:239], v[140:143], v[64:79]
	v_add_u32_e32 v236, s0, v170
	v_add_u32_e32 v237, s97, v170
	v_add3_u32 v236, v236, v166, v160
	v_add3_u32 v238, v237, v165, v160
	ds_read_b64_tr_b16 v[236:237], v236
	ds_read_b64_tr_b16 v[238:239], v238
	s_add_i32 s0, 0, 0x1c600
	s_waitcnt lgkmcnt(4)
	v_mfma_f32_32x32x16_bf16 v[48:63], v[240:243], v[140:143], v[48:63]
	v_add_u32_e32 v240, s0, v170
	v_add_u32_e32 v241, s8, v170
	v_add3_u32 v240, v240, v166, v160
	v_add3_u32 v242, v241, v165, v160
	ds_read_b64_tr_b16 v[240:241], v240
	ds_read_b64_tr_b16 v[242:243], v242
	s_add_i32 s0, 0, 0x1a000
	s_waitcnt lgkmcnt(4)
	v_mfma_f32_32x32x16_bf16 v[32:47], v[232:235], v[140:143], v[32:47]
	v_add_u32_e32 v232, s9, v170
	v_add_u32_e32 v233, s10, v170
	v_add3_u32 v232, v232, v166, v160
	v_add3_u32 v234, v233, v165, v160
	ds_read_b64_tr_b16 v[232:233], v232
	ds_read_b64_tr_b16 v[234:235], v234
	s_waitcnt lgkmcnt(4)
	v_mfma_f32_32x32x16_bf16 v[16:31], v[236:239], v[140:143], v[16:31]
	v_add_u32_e32 v236, s11, v170
	v_add_u32_e32 v237, s18, v170
	v_add3_u32 v236, v236, v166, v160
	v_add3_u32 v238, v237, v165, v160
	ds_read_b64_tr_b16 v[236:237], v236
	ds_read_b64_tr_b16 v[238:239], v238
	s_waitcnt lgkmcnt(4)
	v_mfma_f32_32x32x16_bf16 v[0:15], v[240:243], v[140:143], v[0:15]
	v_add_u32_e32 v240, s19, v170
	v_add_u32_e32 v241, s34, v170
	v_add3_u32 v240, v240, v166, v160
	v_add3_u32 v242, v241, v165, v160
	ds_read_b64_tr_b16 v[240:241], v240
	ds_read_b64_tr_b16 v[242:243], v242
	s_waitcnt lgkmcnt(4)
	v_mfma_f32_32x32x16_bf16 v[112:127], v[232:235], v[136:139], v[112:127]
	v_add_u32_e32 v232, s20, v170
	v_add_u32_e32 v233, s21, v170
	v_add3_u32 v232, v232, v166, v160
	v_add3_u32 v234, v233, v165, v160
	ds_read_b64_tr_b16 v[232:233], v232
	ds_read_b64_tr_b16 v[234:235], v234
	s_waitcnt lgkmcnt(4)
	v_mfma_f32_32x32x16_bf16 v[96:111], v[236:239], v[136:139], v[96:111]
	v_add_u32_e32 v236, s22, v170
	v_add_u32_e32 v237, s23, v170
	v_add3_u32 v236, v236, v166, v160
	v_add3_u32 v238, v237, v165, v160
	ds_read_b64_tr_b16 v[236:237], v236
	ds_read_b64_tr_b16 v[238:239], v238
	s_waitcnt lgkmcnt(4)
; #define MFMA32(a, b, c) __builtin_amdgcn_mfma_f32_32x32x16_bf16((a), (b), (c), 0, 0, 0)
; DI void xattn_unit(const bf16_t* __restrict__ Qg, const bf16_t* __restrict__ Kg, const bf16_t* __restrict__ Vg, bf16_t* __restrict__ Og, lds_t* shm) {
;     ...
; #pragma unroll
;   for (int t = 0; t < 4; ++t) {
;     if (t == 1) { __builtin_amdgcn_sched_barrier(0); asm volatile("s_waitcnt vmcnt(0)" ::: "memory"); __syncthreads(); __builtin_amdgcn_sched_barrier(0); }
;     const unsigned vbase = (t == 0) ? 131072u : (unsigned)t * 32768u;
; #pragma unroll
;     for (int ks = 0; ks < 4; ++ks)
; #pragma unroll
;       for (int c = 0; c < NC; ++c) {
;         const unsigned vo = vbase + (c >> 2) * 16384 + 512 * (c & 3) + 4096 * ks;
;         const bf16x8 vf = tr_pair(shm + vo + va0, shm + vo + 2048 + va1);
;         O[c] = MFMA32(vf, P[t][ks >> 1][ks & 1], O[c]);
;       }
;   }
	v_mfma_f32_32x32x16_bf16 v[80:95], v[240:243], v[136:139], v[80:95]
	v_add_u32_e32 v240, s3, v170
	v_add_u32_e32 v241, s15, v170
	v_add3_u32 v240, v240, v166, v160
	v_add3_u32 v242, v241, v165, v160
	ds_read_b64_tr_b16 v[240:241], v240
	ds_read_b64_tr_b16 v[242:243], v242
	s_waitcnt lgkmcnt(4)
	v_mfma_f32_32x32x16_bf16 v[64:79], v[232:235], v[136:139], v[64:79]
	v_add_u32_e32 v232, s35, v170
	v_add_u32_e32 v233, s40, v170
	v_add3_u32 v232, v232, v166, v160
	v_add3_u32 v234, v233, v165, v160
	ds_read_b64_tr_b16 v[232:233], v232
	ds_read_b64_tr_b16 v[234:235], v234
	s_waitcnt lgkmcnt(4)
	v_mfma_f32_32x32x16_bf16 v[48:63], v[236:239], v[136:139], v[48:63]
	v_add_u32_e32 v236, s41, v170
	v_add_u32_e32 v237, s42, v170
	v_add3_u32 v236, v236, v166, v160
	v_add3_u32 v238, v237, v165, v160
	ds_read_b64_tr_b16 v[236:237], v236
	ds_read_b64_tr_b16 v[238:239], v238
	s_waitcnt lgkmcnt(4)
	v_mfma_f32_32x32x16_bf16 v[32:47], v[240:243], v[136:139], v[32:47]
	v_add_u32_e32 v240, s0, v170
	v_add_u32_e32 v241, s43, v170
	v_add3_u32 v240, v240, v166, v160
	v_add3_u32 v242, v241, v165, v160
	ds_read_b64_tr_b16 v[240:241], v240
	ds_read_b64_tr_b16 v[242:243], v242
	s_add_i32 s0, 0, 0x1a200
	s_waitcnt lgkmcnt(4)
	v_mfma_f32_32x32x16_bf16 v[16:31], v[232:235], v[136:139], v[16:31]
	v_add_u32_e32 v232, s0, v170
	v_add_u32_e32 v233, s46, v170
	v_add3_u32 v232, v232, v166, v160
	v_add3_u32 v234, v233, v165, v160
	ds_read_b64_tr_b16 v[232:233], v232
	ds_read_b64_tr_b16 v[234:235], v234
	s_add_i32 s0, 0, 0x1a400
	s_waitcnt lgkmcnt(4)
	v_mfma_f32_32x32x16_bf16 v[0:15], v[236:239], v[136:139], v[0:15]
	v_add_u32_e32 v236, s0, v170
	v_add_u32_e32 v237, s47, v170
	v_add3_u32 v236, v236, v166, v160
	v_add3_u32 v238, v237, v165, v160
	ds_read_b64_tr_b16 v[236:237], v236
	ds_read_b64_tr_b16 v[238:239], v238
	s_add_i32 s0, 0, 0x1a600
	s_waitcnt lgkmcnt(4)
	v_mfma_f32_32x32x16_bf16 v[112:127], v[240:243], v[132:135], v[112:127]
	v_add_u32_e32 v240, s0, v170
	v_add_u32_e32 v241, s48, v170
	v_add3_u32 v240, v240, v166, v160
	v_add3_u32 v242, v241, v165, v160
	ds_read_b64_tr_b16 v[240:241], v240
	ds_read_b64_tr_b16 v[242:243], v242
	s_add_i32 s0, 0, 0x1e000
	s_waitcnt lgkmcnt(4)
	v_mfma_f32_32x32x16_bf16 v[96:111], v[232:235], v[132:135], v[96:111]
	v_add_u32_e32 v232, s0, v170
	v_add_u32_e32 v233, s49, v170
	v_add3_u32 v232, v232, v166, v160
	v_add3_u32 v234, v233, v165, v160
	ds_read_b64_tr_b16 v[232:233], v232
	ds_read_b64_tr_b16 v[234:235], v234
	s_add_i32 s0, 0, 0x1e200
	s_waitcnt lgkmcnt(4)
	v_mfma_f32_32x32x16_bf16 v[80:95], v[236:239], v[132:135], v[80:95]
	v_add_u32_e32 v236, s0, v170
	v_add_u32_e32 v237, s52, v170
	v_add3_u32 v236, v236, v166, v160
	v_add3_u32 v238, v237, v165, v160
	ds_read_b64_tr_b16 v[236:237], v236
	ds_read_b64_tr_b16 v[238:239], v238
	s_add_i32 s0, 0, 0x1e400
	s_waitcnt lgkmcnt(4)
	v_mfma_f32_32x32x16_bf16 v[64:79], v[240:243], v[132:135], v[64:79]
	v_add_u32_e32 v240, s0, v170
	v_add_u32_e32 v241, s53, v170
	v_add3_u32 v240, v240, v166, v160
	v_add3_u32 v242, v241, v165, v160
	ds_read_b64_tr_b16 v[240:241], v240
	ds_read_b64_tr_b16 v[242:243], v242
	s_add_i32 s0, 0, 0x1e600
	s_waitcnt lgkmcnt(4)
	v_mfma_f32_32x32x16_bf16 v[48:63], v[232:235], v[132:135], v[48:63]
	v_add_u32_e32 v232, s0, v170
	v_add_u32_e32 v233, s54, v170
	v_add3_u32 v232, v232, v166, v160
	v_add3_u32 v234, v233, v165, v160
	ds_read_b64_tr_b16 v[232:233], v232
	ds_read_b64_tr_b16 v[234:235], v234
	s_waitcnt lgkmcnt(4)
	v_mfma_f32_32x32x16_bf16 v[32:47], v[236:239], v[132:135], v[32:47]
	v_add_u32_e32 v236, s55, v170
	v_add_u32_e32 v237, s56, v170
	v_add3_u32 v236, v236, v166, v160
	v_add3_u32 v238, v237, v165, v160
	ds_read_b64_tr_b16 v[236:237], v236
	ds_read_b64_tr_b16 v[238:239], v238
	s_waitcnt lgkmcnt(4)
	v_mfma_f32_32x32x16_bf16 v[16:31], v[240:243], v[132:135], v[16:31]
	v_add_u32_e32 v240, s57, v170
	v_add_u32_e32 v241, s58, v170
	v_add3_u32 v240, v240, v166, v160
	v_add3_u32 v242, v241, v165, v160
	ds_read_b64_tr_b16 v[240:241], v240
	ds_read_b64_tr_b16 v[242:243], v242
	s_waitcnt lgkmcnt(4)
	v_mfma_f32_32x32x16_bf16 v[0:15], v[232:235], v[132:135], v[0:15]
	v_add_u32_e32 v232, s59, v170
	v_add_u32_e32 v233, s60, v170
	v_add3_u32 v232, v232, v166, v160
	v_add3_u32 v234, v233, v165, v160
	ds_read_b64_tr_b16 v[232:233], v232
	ds_read_b64_tr_b16 v[234:235], v234
	s_waitcnt lgkmcnt(4)
	v_mfma_f32_32x32x16_bf16 v[112:127], v[236:239], v[128:131], v[112:127]
	v_add_u32_e32 v236, s61, v170
	v_add_u32_e32 v237, s62, v170
	v_add3_u32 v236, v236, v166, v160
	v_add3_u32 v238, v237, v165, v160
	ds_read_b64_tr_b16 v[236:237], v236
	ds_read_b64_tr_b16 v[238:239], v238
	s_waitcnt lgkmcnt(4)
	v_mfma_f32_32x32x16_bf16 v[96:111], v[240:243], v[128:131], v[96:111]
	v_add_u32_e32 v240, s63, v170
	v_add_u32_e32 v241, s64, v170
	v_add3_u32 v240, v240, v166, v160
	v_add3_u32 v242, v241, v165, v160
	ds_read_b64_tr_b16 v[240:241], v240
	ds_read_b64_tr_b16 v[242:243], v242
	s_waitcnt lgkmcnt(4)
	v_mfma_f32_32x32x16_bf16 v[80:95], v[232:235], v[128:131], v[80:95]
	v_add_u32_e32 v232, s65, v170
	v_add_u32_e32 v233, s6, v170
	v_add3_u32 v232, v232, v166, v160
	v_add3_u32 v234, v233, v165, v160
	ds_read_b64_tr_b16 v[232:233], v232
	ds_read_b64_tr_b16 v[234:235], v234
	s_waitcnt lgkmcnt(4)
	v_mfma_f32_32x32x16_bf16 v[64:79], v[236:239], v[128:131], v[64:79]
	v_add_u32_e32 v236, s7, v170
	v_add_u32_e32 v237, s66, v170
	v_add3_u32 v236, v236, v166, v160
	v_add3_u32 v238, v237, v165, v160
	ds_read_b64_tr_b16 v[236:237], v236
	ds_read_b64_tr_b16 v[238:239], v238
	s_waitcnt lgkmcnt(4)
; DI unsigned pk2(float lo, float hi) { bf2_t v = __builtin_convertvector((f32x2){lo, hi}, bf2_t); return __builtin_bit_cast(unsigned, v); }
; #define MFMA32(a, b, c) __builtin_amdgcn_mfma_f32_32x32x16_bf16((a), (b), (c), 0, 0, 0)
; DI void xattn_unit(const bf16_t* __restrict__ Qg, const bf16_t* __restrict__ Kg, const bf16_t* __restrict__ Vg, bf16_t* __restrict__ Og, lds_t* shm) {
;     ...
;     for (int ks = 0; ks < 4; ++ks)
; #pragma unroll
;       for (int c = 0; c < NC; ++c) {
;         const unsigned vo = vbase + (c >> 2) * 16384 + 512 * (c & 3) + 4096 * ks;
;         const bf16x8 vf = tr_pair(shm + vo + va0, shm + vo + 2048 + va1);
;         O[c] = MFMA32(vf, P[t][ks >> 1][ks & 1], O[c]);
;       }
;   }
;   const float inv = 1.0f / l;
;   const unsigned ooff = ((unsigned)l31 * (unsigned)LDQ + 4u * h) * 2u;
; #pragma unroll
;   for (int c = 0; c < NC; ++c)
; #pragma unroll
;     for (int g4 = 0; g4 < 4; ++g4) {
;       u32x2 w; w.x = pk2(O[c][4 * g4 + 0] * inv, O[c][4 * g4 + 1] * inv); w.y = pk2(O[c][4 * g4 + 2] * inv, O[c][4 * g4 + 3] * inv);
	v_mfma_f32_32x32x16_bf16 v[48:63], v[240:243], v[128:131], v[48:63]
	v_add_u32_e32 v240, s16, v170
	v_add_u32_e32 v241, s17, v170
	v_add3_u32 v240, v240, v166, v160
	v_add3_u32 v242, v241, v165, v160
	ds_read_b64_tr_b16 v[240:241], v240
	ds_read_b64_tr_b16 v[242:243], v242
	s_waitcnt lgkmcnt(4)
	v_mfma_f32_32x32x16_bf16 v[32:47], v[232:235], v[128:131], v[32:47]
	s_waitcnt lgkmcnt(2)
	v_mfma_f32_32x32x16_bf16 v[16:31], v[236:239], v[128:131], v[16:31]
	s_waitcnt lgkmcnt(0)
	v_mfma_f32_32x32x16_bf16 v[0:15], v[240:243], v[128:131], v[0:15]
	v_add_f32_e32 v128, v167, v168
	v_div_scale_f32 v129, s[0:1], v128, v128, 1.0
	v_rcp_f32_e32 v130, v129
	v_readlane_b32 s0, v254, 6
	s_mov_b32 s28, s0
	s_mul_i32 s0, s2, s0
	v_fma_f32 v131, -v129, v130, 1.0
	v_fmac_f32_e32 v130, v131, v130
	v_div_scale_f32 v131, vcc, 1.0, v128, 1.0
	v_mul_f32_e32 v132, v131, v130
	v_fma_f32 v133, -v129, v132, v131
	v_fmac_f32_e32 v132, v133, v130
	v_fma_f32 v129, -v129, v132, v131
	v_div_fmas_f32 v129, v129, v130, v132
	v_div_fixup_f32 v128, v129, v128, 1.0
	v_lshl_or_b32 v129, v163, 3, v164
	v_mbcnt_lo_u32_b32 v130, -1, 0
	v_mbcnt_hi_u32_b32 v130, -1, v130
	v_and_b32_e32 v131, 15, v130
	v_lshlrev_b32_e32 v131, 11, v131
	v_bfe_u32 v129, v130, 4, 1
	v_lshlrev_b32_e32 v129, 5, v129
	v_lshrrev_b32_e32 v130, 5, v130
	v_lshlrev_b32_e32 v130, 4, v130
	v_add3_u32 v130, v131, v129, v130
	v_add_u32_e32 v131, 0x8000, v130
	v_pk_mul_f32 v[112:113], v[128:129], v[112:113] op_sel_hi:[0,1]
	v_pk_mul_f32 v[114:115], v[128:129], v[114:115] op_sel_hi:[0,1]
	v_pk_mul_f32 v[116:117], v[128:129], v[116:117] op_sel_hi:[0,1]
	v_pk_mul_f32 v[118:119], v[128:129], v[118:119] op_sel_hi:[0,1]
	v_pk_mul_f32 v[120:121], v[128:129], v[120:121] op_sel_hi:[0,1]
	v_pk_mul_f32 v[122:123], v[128:129], v[122:123] op_sel_hi:[0,1]
	v_pk_mul_f32 v[124:125], v[128:129], v[124:125] op_sel_hi:[0,1]
	v_pk_mul_f32 v[126:127], v[128:129], v[126:127] op_sel_hi:[0,1]
	v_pk_mul_f32 v[96:97], v[128:129], v[96:97] op_sel_hi:[0,1]
	v_pk_mul_f32 v[98:99], v[128:129], v[98:99] op_sel_hi:[0,1]
	v_pk_mul_f32 v[100:101], v[128:129], v[100:101] op_sel_hi:[0,1]
	v_pk_mul_f32 v[102:103], v[128:129], v[102:103] op_sel_hi:[0,1]
	v_pk_mul_f32 v[104:105], v[128:129], v[104:105] op_sel_hi:[0,1]
	v_pk_mul_f32 v[106:107], v[128:129], v[106:107] op_sel_hi:[0,1]
	v_pk_mul_f32 v[108:109], v[128:129], v[108:109] op_sel_hi:[0,1]
	v_pk_mul_f32 v[110:111], v[128:129], v[110:111] op_sel_hi:[0,1]
	v_pk_mul_f32 v[80:81], v[128:129], v[80:81] op_sel_hi:[0,1]
	v_pk_mul_f32 v[82:83], v[128:129], v[82:83] op_sel_hi:[0,1]
	v_pk_mul_f32 v[84:85], v[128:129], v[84:85] op_sel_hi:[0,1]
	v_pk_mul_f32 v[86:87], v[128:129], v[86:87] op_sel_hi:[0,1]
	v_pk_mul_f32 v[88:89], v[128:129], v[88:89] op_sel_hi:[0,1]
	v_pk_mul_f32 v[90:91], v[128:129], v[90:91] op_sel_hi:[0,1]
	v_pk_mul_f32 v[92:93], v[128:129], v[92:93] op_sel_hi:[0,1]
	v_pk_mul_f32 v[94:95], v[128:129], v[94:95] op_sel_hi:[0,1]
	v_pk_mul_f32 v[64:65], v[128:129], v[64:65] op_sel_hi:[0,1]
	v_pk_mul_f32 v[66:67], v[128:129], v[66:67] op_sel_hi:[0,1]
	v_pk_mul_f32 v[68:69], v[128:129], v[68:69] op_sel_hi:[0,1]
	v_pk_mul_f32 v[70:71], v[128:129], v[70:71] op_sel_hi:[0,1]
	v_pk_mul_f32 v[72:73], v[128:129], v[72:73] op_sel_hi:[0,1]
	v_pk_mul_f32 v[74:75], v[128:129], v[74:75] op_sel_hi:[0,1]
	v_pk_mul_f32 v[76:77], v[128:129], v[76:77] op_sel_hi:[0,1]
	v_pk_mul_f32 v[78:79], v[128:129], v[78:79] op_sel_hi:[0,1]
	v_pk_mul_f32 v[48:49], v[128:129], v[48:49] op_sel_hi:[0,1]
	v_pk_mul_f32 v[50:51], v[128:129], v[50:51] op_sel_hi:[0,1]
	v_pk_mul_f32 v[52:53], v[128:129], v[52:53] op_sel_hi:[0,1]
	v_pk_mul_f32 v[54:55], v[128:129], v[54:55] op_sel_hi:[0,1]
	v_pk_mul_f32 v[56:57], v[128:129], v[56:57] op_sel_hi:[0,1]
	v_pk_mul_f32 v[58:59], v[128:129], v[58:59] op_sel_hi:[0,1]
	v_pk_mul_f32 v[60:61], v[128:129], v[60:61] op_sel_hi:[0,1]
	v_pk_mul_f32 v[62:63], v[128:129], v[62:63] op_sel_hi:[0,1]
	v_pk_mul_f32 v[32:33], v[128:129], v[32:33] op_sel_hi:[0,1]
	v_pk_mul_f32 v[34:35], v[128:129], v[34:35] op_sel_hi:[0,1]
	v_pk_mul_f32 v[36:37], v[128:129], v[36:37] op_sel_hi:[0,1]
	v_pk_mul_f32 v[38:39], v[128:129], v[38:39] op_sel_hi:[0,1]
	v_pk_mul_f32 v[40:41], v[128:129], v[40:41] op_sel_hi:[0,1]
	v_pk_mul_f32 v[42:43], v[128:129], v[42:43] op_sel_hi:[0,1]
	v_pk_mul_f32 v[44:45], v[128:129], v[44:45] op_sel_hi:[0,1]
	v_pk_mul_f32 v[46:47], v[128:129], v[46:47] op_sel_hi:[0,1]
	v_pk_mul_f32 v[16:17], v[128:129], v[16:17] op_sel_hi:[0,1]
	v_pk_mul_f32 v[18:19], v[128:129], v[18:19] op_sel_hi:[0,1]
	v_pk_mul_f32 v[20:21], v[128:129], v[20:21] op_sel_hi:[0,1]
	v_pk_mul_f32 v[22:23], v[128:129], v[22:23] op_sel_hi:[0,1]
	v_pk_mul_f32 v[24:25], v[128:129], v[24:25] op_sel_hi:[0,1]
	v_pk_mul_f32 v[26:27], v[128:129], v[26:27] op_sel_hi:[0,1]
	v_pk_mul_f32 v[28:29], v[128:129], v[28:29] op_sel_hi:[0,1]
	v_pk_mul_f32 v[30:31], v[128:129], v[30:31] op_sel_hi:[0,1]
	v_pk_mul_f32 v[0:1], v[128:129], v[0:1] op_sel_hi:[0,1]
	v_pk_mul_f32 v[2:3], v[128:129], v[2:3] op_sel_hi:[0,1]
	v_pk_mul_f32 v[4:5], v[128:129], v[4:5] op_sel_hi:[0,1]
	v_pk_mul_f32 v[6:7], v[128:129], v[6:7] op_sel_hi:[0,1]
	v_pk_mul_f32 v[8:9], v[128:129], v[8:9] op_sel_hi:[0,1]
	v_pk_mul_f32 v[10:11], v[128:129], v[10:11] op_sel_hi:[0,1]
	v_pk_mul_f32 v[12:13], v[128:129], v[12:13] op_sel_hi:[0,1]
	v_pk_mul_f32 v[14:15], v[128:129], v[14:15] op_sel_hi:[0,1]
	v_cvt_pk_bf16_f32 v112, v112, v113
	v_cvt_pk_bf16_f32 v113, v114, v115
	v_cvt_pk_bf16_f32 v114, v116, v117
	v_cvt_pk_bf16_f32 v115, v118, v119
; DI unsigned pk2(float lo, float hi) { bf2_t v = __builtin_convertvector((f32x2){lo, hi}, bf2_t); return __builtin_bit_cast(unsigned, v); }
; DI void xattn_unit(const bf16_t* __restrict__ Qg, const bf16_t* __restrict__ Kg, const bf16_t* __restrict__ Vg, bf16_t* __restrict__ Og, lds_t* shm) {
;     ...
;   const float inv = 1.0f / l;
;   const unsigned ooff = ((unsigned)l31 * (unsigned)LDQ + 4u * h) * 2u;
; #pragma unroll
;   for (int c = 0; c < NC; ++c)
; #pragma unroll
;     for (int g4 = 0; g4 < 4; ++g4) {
;       u32x2 w; w.x = pk2(O[c][4 * g4 + 0] * inv, O[c][4 * g4 + 1] * inv); w.y = pk2(O[c][4 * g4 + 2] * inv, O[c][4 * g4 + 3] * inv);
;       gst<u32x2>(Og + 32 * c + 8 * g4, ooff, w);
;     }
; DI void cross_attn_own_tiles(const Params& p, lds_t* shm) {
;     ...
;     int pm, pn; if (!g8::tile_coords(i * (int)gridDim.x + (int)blockIdx.x, T_TOK / 256, 4, pm, pn)) break;
	v_cvt_pk_bf16_f32 v120, v120, v121
	v_cvt_pk_bf16_f32 v121, v122, v123
	v_cvt_pk_bf16_f32 v122, v124, v125
	v_cvt_pk_bf16_f32 v123, v126, v127
	s_nop 1
	v_permlane32_swap_b32_e32 v112, v114
	v_permlane32_swap_b32_e32 v113, v115
	v_permlane32_swap_b32_e32 v120, v122
	v_permlane32_swap_b32_e32 v121, v123
	s_nop 1
	v_permlane16_swap_b32_e32 v112, v120
	v_permlane16_swap_b32_e32 v113, v121
	v_permlane16_swap_b32_e32 v114, v122
	v_permlane16_swap_b32_e32 v115, v123
	global_store_dwordx4 v130, v[112:115], s[30:31]
	global_store_dwordx4 v131, v[120:123], s[30:31]
	v_cvt_pk_bf16_f32 v96, v96, v97
	v_cvt_pk_bf16_f32 v97, v98, v99
	v_cvt_pk_bf16_f32 v98, v100, v101
	v_cvt_pk_bf16_f32 v99, v102, v103
	v_cvt_pk_bf16_f32 v104, v104, v105
	v_cvt_pk_bf16_f32 v105, v106, v107
	v_cvt_pk_bf16_f32 v106, v108, v109
	v_cvt_pk_bf16_f32 v107, v110, v111
	s_nop 1
	v_permlane32_swap_b32_e32 v96, v98
	v_permlane32_swap_b32_e32 v97, v99
	v_permlane32_swap_b32_e32 v104, v106
	v_permlane32_swap_b32_e32 v105, v107
	s_nop 1
	v_permlane16_swap_b32_e32 v96, v104
	v_permlane16_swap_b32_e32 v97, v105
	v_permlane16_swap_b32_e32 v98, v106
	v_permlane16_swap_b32_e32 v99, v107
	global_store_dwordx4 v130, v[96:99], s[30:31] offset:64
	global_store_dwordx4 v131, v[104:107], s[30:31] offset:64
	v_cvt_pk_bf16_f32 v80, v80, v81
	v_cvt_pk_bf16_f32 v81, v82, v83
	v_cvt_pk_bf16_f32 v82, v84, v85
	v_cvt_pk_bf16_f32 v83, v86, v87
	v_cvt_pk_bf16_f32 v88, v88, v89
	v_cvt_pk_bf16_f32 v89, v90, v91
	v_cvt_pk_bf16_f32 v90, v92, v93
	v_cvt_pk_bf16_f32 v91, v94, v95
	s_nop 1
	v_permlane32_swap_b32_e32 v80, v82
	v_permlane32_swap_b32_e32 v81, v83
	v_permlane32_swap_b32_e32 v88, v90
	v_permlane32_swap_b32_e32 v89, v91
	s_nop 1
	v_permlane16_swap_b32_e32 v80, v88
	v_permlane16_swap_b32_e32 v81, v89
	v_permlane16_swap_b32_e32 v82, v90
	v_permlane16_swap_b32_e32 v83, v91
	global_store_dwordx4 v130, v[80:83], s[30:31] offset:128
	global_store_dwordx4 v131, v[88:91], s[30:31] offset:128
	v_cvt_pk_bf16_f32 v64, v64, v65
	v_cvt_pk_bf16_f32 v65, v66, v67
	v_cvt_pk_bf16_f32 v66, v68, v69
	v_cvt_pk_bf16_f32 v67, v70, v71
	v_cvt_pk_bf16_f32 v72, v72, v73
	v_cvt_pk_bf16_f32 v73, v74, v75
	v_cvt_pk_bf16_f32 v74, v76, v77
	v_cvt_pk_bf16_f32 v75, v78, v79
	s_nop 1
	v_permlane32_swap_b32_e32 v64, v66
	v_permlane32_swap_b32_e32 v65, v67
	v_permlane32_swap_b32_e32 v72, v74
	v_permlane32_swap_b32_e32 v73, v75
	s_nop 1
	v_permlane16_swap_b32_e32 v64, v72
	v_permlane16_swap_b32_e32 v65, v73
	v_permlane16_swap_b32_e32 v66, v74
	v_permlane16_swap_b32_e32 v67, v75
	global_store_dwordx4 v130, v[64:67], s[30:31] offset:192
	global_store_dwordx4 v131, v[72:75], s[30:31] offset:192
	v_cvt_pk_bf16_f32 v48, v48, v49
	v_cvt_pk_bf16_f32 v49, v50, v51
	v_cvt_pk_bf16_f32 v50, v52, v53
	v_cvt_pk_bf16_f32 v51, v54, v55
	v_cvt_pk_bf16_f32 v56, v56, v57
	v_cvt_pk_bf16_f32 v57, v58, v59
	v_cvt_pk_bf16_f32 v58, v60, v61
	v_cvt_pk_bf16_f32 v59, v62, v63
	s_nop 1
	v_permlane32_swap_b32_e32 v48, v50
	v_permlane32_swap_b32_e32 v49, v51
	v_permlane32_swap_b32_e32 v56, v58
	v_permlane32_swap_b32_e32 v57, v59
	s_nop 1
	v_permlane16_swap_b32_e32 v48, v56
	v_permlane16_swap_b32_e32 v49, v57
	v_permlane16_swap_b32_e32 v50, v58
	v_permlane16_swap_b32_e32 v51, v59
	global_store_dwordx4 v130, v[48:51], s[30:31] offset:256
	global_store_dwordx4 v131, v[56:59], s[30:31] offset:256
	v_cvt_pk_bf16_f32 v32, v32, v33
	v_cvt_pk_bf16_f32 v33, v34, v35
	v_cvt_pk_bf16_f32 v34, v36, v37
	v_cvt_pk_bf16_f32 v35, v38, v39
	v_cvt_pk_bf16_f32 v40, v40, v41
	v_cvt_pk_bf16_f32 v41, v42, v43
	v_cvt_pk_bf16_f32 v42, v44, v45
	v_cvt_pk_bf16_f32 v43, v46, v47
	s_nop 1
	v_permlane32_swap_b32_e32 v32, v34
	v_permlane32_swap_b32_e32 v33, v35
	v_permlane32_swap_b32_e32 v40, v42
	v_permlane32_swap_b32_e32 v41, v43
	s_nop 1
	v_permlane16_swap_b32_e32 v32, v40
	v_permlane16_swap_b32_e32 v33, v41
	v_permlane16_swap_b32_e32 v34, v42
	v_permlane16_swap_b32_e32 v35, v43
	global_store_dwordx4 v130, v[32:35], s[30:31] offset:320
	global_store_dwordx4 v131, v[40:43], s[30:31] offset:320
	v_cvt_pk_bf16_f32 v16, v16, v17
	v_cvt_pk_bf16_f32 v17, v18, v19
	v_cvt_pk_bf16_f32 v18, v20, v21
	v_cvt_pk_bf16_f32 v19, v22, v23
	v_cvt_pk_bf16_f32 v24, v24, v25
	v_cvt_pk_bf16_f32 v25, v26, v27
	v_cvt_pk_bf16_f32 v26, v28, v29
	v_cvt_pk_bf16_f32 v27, v30, v31
	s_nop 1
	v_permlane32_swap_b32_e32 v16, v18
	v_permlane32_swap_b32_e32 v17, v19
	v_permlane32_swap_b32_e32 v24, v26
	v_permlane32_swap_b32_e32 v25, v27
	s_nop 1
	v_permlane16_swap_b32_e32 v16, v24
	v_permlane16_swap_b32_e32 v17, v25
	v_permlane16_swap_b32_e32 v18, v26
	v_permlane16_swap_b32_e32 v19, v27
	global_store_dwordx4 v130, v[16:19], s[30:31] offset:384
	global_store_dwordx4 v131, v[24:27], s[30:31] offset:384
	v_cvt_pk_bf16_f32 v0, v0, v1
	v_cvt_pk_bf16_f32 v1, v2, v3
	v_cvt_pk_bf16_f32 v2, v4, v5
	v_cvt_pk_bf16_f32 v3, v6, v7
	v_cvt_pk_bf16_f32 v8, v8, v9
	v_cvt_pk_bf16_f32 v9, v10, v11
	v_cvt_pk_bf16_f32 v10, v12, v13
	v_cvt_pk_bf16_f32 v11, v14, v15
	s_nop 1
	v_permlane32_swap_b32_e32 v0, v2
	v_permlane32_swap_b32_e32 v1, v3
	v_permlane32_swap_b32_e32 v8, v10
	v_permlane32_swap_b32_e32 v9, v11
	s_nop 1
	v_permlane16_swap_b32_e32 v0, v8
	v_permlane16_swap_b32_e32 v1, v9
	v_permlane16_swap_b32_e32 v2, v10
	v_permlane16_swap_b32_e32 v3, v11
	global_store_dwordx4 v130, v[0:3], s[30:31] offset:448
	global_store_dwordx4 v131, v[8:11], s[30:31] offset:448
	s_add_i32 s0, s0, s68
	s_add_i32 s33, s33, s28
	s_cmpk_lt_i32 s33, 0x200
	v_readlane_b32 s1, v254, 7
	s_cbranch_scc0 .LBB0_634
